# packed-f32 scan blocks (v_pk_mul/fma), KSPLIT 896
# speedup vs baseline: 1.0028x; 1.0028x over previous
; #define WSB_DECL unsigned char* wsb = A.ws; asm volatile("" : "+s"(wsb))
; __global__ void __launch_bounds__(NWAVES * 64, 2) hybrid_fwd(Args A) {
;     ...
;     for (int ph = lo; ph < hi; ++ph) {
;       const int l = (ph - 1) / 6, s = (ph == 0) ? -1 : (ph - 1) % 6;
;       WSB_DECL;
;       const int reps = ((ph > 0 && ((DUP_MASK >> s) & 1) && !(s == 5 && l == DEPTH - 1)) || (ph == 0 && (DUP_MASK & 64))) ? 2 : 1;
;       for (int rep = 0; rep < reps; ++rep) {
;         if (rep) { if (ph == 0) cg::this_grid().sync(); else xcd_barrier(bar); }
;         if (ph == 0) { if (EN(0)) phase_prologue(A, C); }
;         else {
;             if (s == 0 && EN(1)) { pg8::Gemm g{WS_PTR(const bf16, WS_HB), WS_PTR(const bf16, WS_WINT) + (size_t)l * DINP * D, M, DINP, D, D}; pg8::StaticOrder S; S.init(M, DINP, C.G, C.bid);
;                 pg8::EpiU E{WS_PTR(bf16, WS_U), WS_PTR(const float, WS_SS) + (size_t)l * M};
;                 pg8::gemm_phase<pg8::EpiU, pg8::StaticOrder, G1_ALIGN, G1_SP2>(C.lds, g, S, E); }
;             else if (s == 1 && EN(2)) phase_prep(A, C, l);
;             else if ((s == 2 && EN(3)) || (s == 3 && EN(4)) || (s == 4 && EN(5))) {
;                 const bool split = C.G >= 192; bool go = (s == 4); int k0 = split ? KSPLIT : 0, kl = D - k0, gg = C.G, cc = C.bid, mrows = M; size_t roff = 0;
;                 if (s == 2) { go = phase_mixers(A, C, l, rep ? DUP_UN : 7); k0 = 0; kl = KSPLIT; gg = C.G - 128; cc = C.bid - 128; mrows = MP; }
;                 if (s == 3) { phase_post(A, C, l, split ? 8 : 0); go = split && C.bid < 8 && !rep; k0 = 0; kl = KSPLIT; gg = 8; cc = C.bid; mrows = MS; roff = (size_t)MP * D; }
;                 if (go) { pg8::Gemm g{WS_PTR(const bf16, WS_XN) + roff + k0, WS_PTR(const bf16, WS_WOUTT) + (size_t)l * D * D + k0, mrows, D, kl, D}; pg8::StaticOrder S; S.init(mrows, D, gg, cc);
;                     const bool first = (l == 0) && (s != 4 || !split);
;                     float* Hout = ((rep && s == 4) ? WS_PTR(float, WS_U) : A.out) + roff;
;                     pg8::EpiResN E{Hout, first ? (s == 3 ? A.in[I_XS] : A.in[I_XP]) : Hout, first ? A.in[I_XS] - (size_t)MP * D : Hout, WS_PTR(bf16, WS_HB), WS_PTR(float, WS_SS) + (size_t)(l + 1) * M, s == 4 && !rep};
;                     pg8::gemm_phase<pg8::EpiResN, pg8::StaticOrder, G2_ALIGN, true>(C.lds, g, S, E); }
.LBB0_14:
	v_readlane_b32 s12, v253, 0
	s_cmpk_lt_i32 s12, 0xb16
	s_cselect_b64 s[2:3], -1, 0
	v_writelane_b32 v253, s2, 11
	s_load_dword s13, s[0:1], 0xe8
	s_load_dwordx4 s[16:19], s[0:1], 0xc0
	s_load_dwordx2 s[14:15], s[0:1], 0xd0
	v_writelane_b32 v253, s3, 12
	s_ashr_i32 s2, s12, 31
	v_writelane_b32 v253, s2, 13
	s_lshr_b32 s2, s2, 29
	s_add_i32 s2, s12, s2
	s_ashr_i32 s9, s2, 3
	s_and_b32 s2, s2, -8
	s_sub_i32 s10, s12, s2
	s_mul_i32 s2, s10, 0x162
	s_add_i32 s11, s2, 6
	s_waitcnt lgkmcnt(0)
	s_ashr_i32 s2, s13, 31
	s_cmpk_lt_i32 s13, 0xc0
	v_writelane_b32 v253, s2, 14
	s_cselect_b64 s[2:3], -1, 0
	v_writelane_b32 v253, s2, 15
	s_cmpk_gt_i32 s13, 0xbf
	s_load_dwordx16 s[80:95], s[0:1], 0x0
	v_writelane_b32 v253, s3, 16
	s_cselect_b64 s[2:3], -1, 0
	s_and_b64 s[6:7], s[2:3], exec
	s_cselect_b32 s7, 8, 0
	s_cselect_b32 s6, 0x380, 0
	v_writelane_b32 v253, s7, 17
	v_writelane_b32 v253, s6, 18
	s_sub_i32 s6, 0x800, s6
	v_writelane_b32 v253, s6, 19
	s_add_u32 s6, s18, 0x10692000
	v_writelane_b32 v253, s6, 20
	s_addc_u32 s6, s19, 0
	v_writelane_b32 v253, s6, 21
	s_add_u32 s6, s18, 0x10200000
	v_writelane_b32 v253, s6, 22
	s_addc_u32 s6, s19, 0
	v_writelane_b32 v253, s6, 23
	s_add_u32 s6, s18, 0x10bb6000
	v_writelane_b32 v253, s6, 24
	s_addc_u32 s6, s19, 0
	v_writelane_b32 v253, s6, 25
	s_add_u32 s6, s18, 0x10492000
	v_writelane_b32 v253, s6, 26
	s_addc_u32 s6, s19, 0
	s_waitcnt lgkmcnt(0)
	s_cmp_eq_u64 s[92:93], 0
	v_writelane_b32 v253, s6, 27
	s_cselect_b64 s[6:7], -1, 0
	v_writelane_b32 v253, s6, 28
	s_cmp_lg_u64 s[92:93], 0
	s_load_dwordx16 s[36:51], s[0:1], 0x40
	v_writelane_b32 v253, s7, 29
	s_cselect_b64 s[6:7], -1, 0
	v_writelane_b32 v253, s6, 30
	v_mov_b32_e32 v207, 0x260
	v_mov_b32_e32 v229, 0x3727c5ac
	v_writelane_b32 v253, s7, 31
	s_add_u32 s6, s14, 0x8000
	v_writelane_b32 v253, s6, 32
	s_addc_u32 s6, s15, 0
	v_writelane_b32 v253, s6, 33
	s_add_i32 s6, s13, 0xffffff80
	v_writelane_b32 v253, s6, 34
	s_add_i32 s6, s12, 0xffffff80
	s_cmp_lt_i32 s12, 8
	v_writelane_b32 v253, s6, 35
	s_cselect_b64 s[6:7], -1, 0
	s_and_b64 s[2:3], s[6:7], s[2:3]
	v_writelane_b32 v253, s2, 36
	v_mov_b32_e32 v252, 1
	v_mov_b32_e32 v251, 0x7f800000
	v_writelane_b32 v253, s3, 37
	s_add_u32 s2, s82, 0xf0000000
	v_writelane_b32 v253, s2, 38
	s_addc_u32 s2, s83, -1
	s_cmp_lg_u64 s[94:95], 0
	v_writelane_b32 v253, s2, 39
	s_cselect_b64 s[2:3], -1, 0
	v_writelane_b32 v253, s2, 40
	s_cmp_lg_u32 s26, 2
	v_mov_b32_e32 v142, 0x41b17218
	v_writelane_b32 v253, s3, 41
	s_cselect_b64 s[2:3], -1, 0
	v_writelane_b32 v253, s2, 42
	v_mov_b32_e32 v143, 0x3000
	s_movk_i32 s33, 0x7fff
	v_writelane_b32 v253, s3, 43
	s_add_u32 s2, s14, 0x4200
	s_addc_u32 s3, s15, 0
	v_writelane_b32 v253, s2, 44
	s_mov_b32 s96, 0xffff0000
	s_mov_b32 s97, 0x3fb8aa3b
	v_writelane_b32 v253, s3, 45
	s_add_u32 s2, s14, 0x4400
	s_addc_u32 s3, s15, 0
	v_writelane_b32 v253, s2, 46
	s_mov_b32 s20, 0xbfb8aa3b
	s_mov_b32 s21, 0xb2a5705f
	v_writelane_b32 v253, s3, 47
	s_add_u32 s2, s14, 0x4500
	s_addc_u32 s3, s15, 0
	v_writelane_b32 v253, s2, 48
	s_mov_b32 s28, 0x42ce8ed0
	s_mov_b32 s29, 0xc2b17218
	v_writelane_b32 v253, s3, 49
	s_add_u32 s2, s14, 0x4600
	s_addc_u32 s3, s15, 0
	v_writelane_b32 v253, s2, 50
	s_mov_b32 s34, 0x7f800000
	s_mov_b32 s35, 0x800000
	v_writelane_b32 v253, s3, 51
	s_add_u32 s2, s14, 0x4700
	s_addc_u32 s3, s15, 0
	v_writelane_b32 v253, s2, 52
	s_mov_b64 s[22:23], 0x80
	s_nop 0
	v_writelane_b32 v253, s3, 53
	s_add_u32 s2, s14, 0x4800
	s_addc_u32 s3, s15, 0
	v_writelane_b32 v253, s2, 54
	s_nop 1
	v_writelane_b32 v253, s3, 55
	s_add_u32 s2, s14, 0x4900
	s_addc_u32 s3, s15, 0
	v_writelane_b32 v253, s2, 56
	s_nop 1
	v_writelane_b32 v253, s3, 57
	s_add_u32 s2, s14, 0x4a00
	s_addc_u32 s3, s15, 0
	v_writelane_b32 v253, s2, 58
	s_nop 1
	v_writelane_b32 v253, s3, 59
	s_add_u32 s2, s14, 0x4b00
	s_addc_u32 s3, s15, 0
	v_writelane_b32 v253, s2, 60
	s_nop 1
	v_writelane_b32 v253, s3, 61
	s_add_u32 s2, s14, 0x4c00
	s_addc_u32 s3, s15, 0
	v_writelane_b32 v253, s2, 62
	s_nop 1
	v_writelane_b32 v253, s3, 63
	s_add_u32 s2, s14, 0x4d00
	s_addc_u32 s3, s15, 0
	v_writelane_b32 v254, s2, 0
	s_nop 1
	v_writelane_b32 v254, s3, 1
	s_add_u32 s2, s14, 0x4e00
	s_addc_u32 s3, s15, 0
	v_writelane_b32 v254, s2, 2
	s_nop 1
	v_writelane_b32 v254, s3, 3
	s_add_u32 s2, s14, 0x4f00
	s_addc_u32 s3, s15, 0
	v_writelane_b32 v254, s2, 4
	s_nop 1
	v_writelane_b32 v254, s3, 5
	s_add_u32 s2, s14, 0x5000
	s_addc_u32 s3, s15, 0
	v_writelane_b32 v254, s2, 6
	s_nop 1
	v_writelane_b32 v254, s3, 7
	s_add_u32 s2, s14, 0x5100
	s_addc_u32 s3, s15, 0
	v_writelane_b32 v254, s2, 8
	s_nop 1
	v_writelane_b32 v254, s3, 9
	s_add_u32 s2, s14, 0x5200
	s_addc_u32 s3, s15, 0
	v_writelane_b32 v254, s2, 10
	s_nop 1
	v_writelane_b32 v254, s3, 11
	s_add_u32 s2, s14, 0x5300
	s_addc_u32 s3, s15, 0
	v_writelane_b32 v254, s2, 12
	s_cmp_eq_u32 s8, 15
	s_nop 0
	v_writelane_b32 v254, s3, 13
	s_cselect_b64 s[2:3], -1, 0
	v_writelane_b32 v254, s2, 14
	s_cmp_eq_u32 s8, 14
	s_nop 0
	v_writelane_b32 v254, s3, 15
	s_cselect_b64 s[2:3], -1, 0
	v_writelane_b32 v254, s2, 16
	s_cmp_eq_u32 s8, 13
	s_nop 0
	v_writelane_b32 v254, s3, 17
; __device__ __forceinline__ unsigned xb_ld(unsigned* p)              { return __hip_atomic_load(p, __ATOMIC_RELAXED, __HIP_MEMORY_SCOPE_AGENT); }
;     __host__ __device__ bool next(int i, Unit& u) const {
;         const long L = (long)i * G + c; if (L >= nwg) return false;
;         int wgid = (int)L; { const int q = nwg / NXCD, r = nwg % NXCD, xcd = wgid % NXCD, off = wgid / NXCD; wgid = (xcd < r ? xcd * (q + 1) : r * (q + 1) + (xcd - r) * q) + off; }
;         const int nig = WGM * nN, gid = wgid / nig, fm = gid * WGM, gsz = (nM - fm) < WGM ? (nM - fm) : WGM;
;         u.pm = fm + ((wgid % nig) % gsz); u.pn = (wgid % nig) / gsz; return true;
; __device__ __forceinline__ void xcd_barrier_complete(unsigned* bar, unsigned x, unsigned& nloc, unsigned& nx) {
;     ...
;     unsigned sum, cnt, mine, sp = 0u;
;     for (;;) {
;         sum = 0u; cnt = 0u; mine = 0u;
; #pragma unroll
;         for (unsigned j = 0; j < 16; ++j) { const unsigned c = xb_ld(&bar[XB_XCNT(j)]); sum += c; cnt += (c > 0u) ? 1u : 0u; mine = (j == x) ? c : mine; }
;         if (sum == G) break;
;         __builtin_amdgcn_s_sleep(1);
;         if ((++sp & 255u) == 0u) { if (xb_ld(&bar[XB_TMO])) break; if (sp > XB_SPIN_CAP) { atomicAdd(&bar[XB_TMO], 1u); break; } }
;     }
;     nloc = mine > 0u ? mine : 1u; nx = cnt > 0u ? cnt : 1u;
	s_cselect_b64 s[2:3], -1, 0
	v_writelane_b32 v254, s2, 18
	s_cmp_eq_u32 s8, 12
	s_nop 0
	v_writelane_b32 v254, s3, 19
	s_cselect_b64 s[2:3], -1, 0
	v_writelane_b32 v254, s2, 20
	s_cmp_eq_u32 s8, 11
	s_nop 0
	v_writelane_b32 v254, s3, 21
	s_cselect_b64 s[2:3], -1, 0
	v_writelane_b32 v254, s2, 22
	s_cmp_eq_u32 s8, 10
	s_nop 0
	v_writelane_b32 v254, s3, 23
	s_cselect_b64 s[2:3], -1, 0
	v_writelane_b32 v254, s2, 24
	s_cmp_eq_u32 s8, 9
	s_nop 0
	v_writelane_b32 v254, s3, 25
	s_cselect_b64 s[2:3], -1, 0
	v_writelane_b32 v254, s2, 26
	s_cmp_eq_u32 s8, 8
	s_nop 0
	v_writelane_b32 v254, s3, 27
	s_cselect_b64 s[2:3], -1, 0
	v_writelane_b32 v254, s2, 28
	s_cmp_eq_u32 s8, 7
	s_nop 0
	v_writelane_b32 v254, s3, 29
	s_cselect_b64 s[2:3], -1, 0
	v_writelane_b32 v254, s2, 30
	s_cmp_eq_u32 s8, 6
	s_nop 0
	v_writelane_b32 v254, s3, 31
	s_cselect_b64 s[2:3], -1, 0
	v_writelane_b32 v254, s2, 32
	s_cmp_eq_u32 s8, 5
	s_nop 0
	v_writelane_b32 v254, s3, 33
	s_cselect_b64 s[2:3], -1, 0
	v_writelane_b32 v254, s2, 34
	s_cmp_eq_u32 s8, 4
	s_nop 0
	v_writelane_b32 v254, s3, 35
	s_cselect_b64 s[2:3], -1, 0
	v_writelane_b32 v254, s2, 36
	s_cmp_eq_u32 s8, 3
	s_nop 0
	v_writelane_b32 v254, s3, 37
	s_cselect_b64 s[2:3], -1, 0
	v_writelane_b32 v254, s2, 38
	s_cmp_eq_u32 s8, 2
	s_nop 0
	v_writelane_b32 v254, s3, 39
	s_cselect_b64 s[2:3], -1, 0
	v_writelane_b32 v254, s2, 40
	s_cmp_eq_u32 s8, 1
	s_nop 0
	v_writelane_b32 v254, s3, 41
	s_cselect_b64 s[2:3], -1, 0
	v_writelane_b32 v254, s2, 42
	s_cmp_eq_u32 s8, 0
	s_nop 0
	v_writelane_b32 v254, s3, 43
	s_cselect_b64 s[2:3], -1, 0
	v_writelane_b32 v254, s2, 44
	s_nop 1
	v_writelane_b32 v254, s3, 45
	s_lshl_b32 s2, s8, 8
	s_add_u32 s2, s4, s2
	s_addc_u32 s3, s5, 0
	s_add_u32 s4, s2, 0x1400
	s_addc_u32 s5, s3, 0
	v_writelane_b32 v254, s4, 46
	s_add_u32 s2, s2, 0x2400
	s_addc_u32 s3, s3, 0
	v_writelane_b32 v254, s5, 47
	v_writelane_b32 v254, s2, 48
	s_nop 1
	v_writelane_b32 v254, s3, 49
	s_add_u32 s2, s14, 0x7400
	s_addc_u32 s3, s15, 0
	v_writelane_b32 v254, s2, 50
	s_nop 1
	v_writelane_b32 v254, s3, 51
	s_add_u32 s2, s14, 0x7500
	s_addc_u32 s3, s15, 0
	v_writelane_b32 v254, s2, 52
	s_cmp_lt_i32 s10, 6
	s_mulk_i32 s10, 0x163
	v_writelane_b32 v254, s3, 53
	s_cselect_b32 s2, s10, s11
	s_add_i32 s2, s2, s9
	s_mul_hi_i32 s3, s2, 0x2e8ba2e9
	s_lshr_b32 s4, s3, 31
	s_ashr_i32 s3, s3, 5
	s_add_i32 s3, s3, s4
	s_mul_i32 s4, s3, 0xb0
	s_lshl_b32 s5, s3, 3
	s_sub_i32 s4, s2, s4
	s_sub_i32 s2, 0x81, s5
	s_min_u32 s6, s2, 8
	v_cvt_f32_ubyte0_e32 v2, s6
	v_cvt_f32_i32_e32 v1, s4
	v_rcp_iflag_f32_e32 v3, v2
	s_ashr_i32 s2, s4, 30
	s_or_b32 s7, s2, 1
	v_mul_f32_e32 v3, v1, v3
	v_trunc_f32_e32 v3, v3
	v_fma_f32 v1, -v3, v2, v1
	v_cmp_ge_f32_e64 s[2:3], |v1|, v2
	v_lshrrev_b32_e32 v1, 20, v0
	v_lshrrev_b32_e32 v0, 10, v0
	v_or_b32_e32 v0, v0, v1
	v_cvt_i32_f32_e32 v1, v3
	s_and_b64 s[2:3], s[2:3], exec
	s_movk_i32 s2, 0x3ff
	v_and_or_b32 v0, v0, s2, v185
	s_cselect_b32 s2, s7, 0
	v_readfirstlane_b32 s3, v1
	s_add_i32 s2, s3, s2
	s_mul_i32 s3, s2, s6
	s_sub_i32 s3, s4, s3
	s_sext_i32_i16 s3, s3
	s_add_i32 s3, s5, s3
	v_writelane_b32 v254, s3, 54
	s_sext_i32_i16 s2, s2
	v_writelane_b32 v254, s2, 55
	s_add_u32 s2, s14, 0xfc54300
	s_addc_u32 s3, s15, 0
	v_writelane_b32 v254, s2, 56
	v_mov_b32_e32 v1, 0
	v_mov_b32_e32 v98, v1
	v_writelane_b32 v254, s3, 57
	s_add_u32 s2, s14, 0xfc3c000
	v_writelane_b32 v254, s2, 58
	s_addc_u32 s2, s15, 0
	v_writelane_b32 v254, s2, 59
	s_add_i32 s2, 0, 0xd000
	v_writelane_b32 v254, s2, 60
	s_add_i32 s2, 0, 0x3cf0
	v_writelane_b32 v254, s2, 61
	s_mov_b32 s3, 0
	v_writelane_b32 v254, s2, 62
	v_mov_b32_e32 v99, v1
	v_mov_b32_e32 v100, v1
	v_writelane_b32 v254, s3, 63
	v_cmp_eq_u32_e64 s[2:3], 0, v185
	v_mov_b32_e32 v101, v1
	s_mov_b32 s4, 0x3f317217
	v_writelane_b32 v255, s2, 0
	s_mov_b32 s5, 0xc2ce8ed0
	s_mov_b32 s6, 0x42b17218
	v_writelane_b32 v255, s3, 1
	v_cmp_eq_u32_e64 s[2:3], 0, v0
	s_mov_b32 s7, 0xf800000
	s_nop 0
	v_writelane_b32 v255, s2, 2
	s_nop 1
	v_writelane_b32 v255, s3, 3
	s_waitcnt lgkmcnt(0)
	v_writelane_b32 v255, s36, 4
	s_nop 1
	v_writelane_b32 v255, s37, 5
	v_writelane_b32 v255, s38, 6
	v_writelane_b32 v255, s39, 7
	v_writelane_b32 v255, s40, 8
	v_writelane_b32 v255, s41, 9
	v_writelane_b32 v255, s42, 10
	v_writelane_b32 v255, s43, 11
	v_writelane_b32 v255, s44, 12
	v_writelane_b32 v255, s45, 13
	v_writelane_b32 v255, s46, 14
	v_writelane_b32 v255, s47, 15
	v_writelane_b32 v255, s48, 16
	v_writelane_b32 v255, s49, 17
	v_writelane_b32 v255, s50, 18
	v_writelane_b32 v255, s51, 19
	s_load_dwordx16 s[36:51], s[0:1], 0x80
	s_waitcnt lgkmcnt(0)
	v_writelane_b32 v255, s36, 20
	s_nop 1
	v_writelane_b32 v255, s37, 21
	v_writelane_b32 v255, s38, 22
	v_writelane_b32 v255, s39, 23
	v_writelane_b32 v255, s40, 24
	v_writelane_b32 v255, s41, 25
	v_writelane_b32 v255, s42, 26
	v_writelane_b32 v255, s43, 27
	v_writelane_b32 v255, s44, 28
	v_writelane_b32 v255, s45, 29
	v_writelane_b32 v255, s46, 30
	v_writelane_b32 v255, s47, 31
	v_writelane_b32 v255, s48, 32
	v_writelane_b32 v255, s49, 33
	v_writelane_b32 v255, s50, 34
	v_writelane_b32 v255, s51, 35
	s_branch .LBB0_19

.LBB0_685:
	v_mov_b32 v138, v2
	v_mov_b32 v139, v13
	v_mov_b32 v140, v12
	v_mov_b32 v141, v8
	ds_read_b128 v[164:167], v5 offset:0
	ds_read_b128 v[168:171], v5 offset:256
	ds_read_b128 v[172:175], v5 offset:512
	ds_read_b128 v[176:179], v5 offset:768
	ds_read_b128 v[180:183], v5 offset:1024
	ds_read_b32 v184, v9 offset:0
	ds_read_b128 v[186:189], v5 offset:1536
	ds_read_b128 v[190:193], v5 offset:1792
	ds_read_b128 v[194:197], v5 offset:2048
	ds_read_b128 v[198:201], v5 offset:2304
	ds_read_b128 v[202:205], v5 offset:2560
	ds_read_b32 v206, v9 offset:1536
	s_waitcnt lgkmcnt(0)
	v_pk_mul_f32 v[144:145], v[138:139], v[164:165]
	v_pk_fma_f32 v[144:145], v[140:141], v[166:167], v[144:145]
	v_add_f32 v146, v144, v145
	ds_read_b128 v[208:211], v5 offset:3072
	ds_read_b128 v[212:215], v5 offset:3328
	ds_read_b128 v[216:219], v5 offset:3584
	ds_read_b128 v[220:223], v5 offset:3840
	ds_read_b128 v[224:227], v5 offset:4096
	ds_read_b32 v228, v9 offset:3072
	v_add_f32_dpp v146, v146, v146 quad_perm:[1,0,3,2] row_mask:0xf bank_mask:0xf bound_ctrl:1
	s_nop 0
	s_nop 0
	v_add_f32_dpp v146, v146, v146 quad_perm:[2,3,0,1] row_mask:0xf bank_mask:0xf bound_ctrl:1
	s_nop 0
	v_pk_mul_f32 v[176:177], v[176:177], v[184:185] op_sel_hi:[1,0]
	v_add_f32_dpp v146, v146, v146 row_half_mirror row_mask:0xf bank_mask:0xf bound_ctrl:1
	v_pk_mul_f32 v[178:179], v[178:179], v[184:185] op_sel_hi:[1,0]
	s_waitcnt lgkmcnt(6)
	v_add_f32_dpp v146, v146, v146 row_mirror row_mask:0xf bank_mask:0xf bound_ctrl:1
	v_pk_fma_f32 v[176:177], v[146:147], v[168:169], v[176:177] op_sel_hi:[0,1,1] neg_lo:[1,0,0] neg_hi:[1,0,0]
	v_pk_fma_f32 v[178:179], v[146:147], v[170:171], v[178:179] op_sel_hi:[0,1,1] neg_lo:[1,0,0] neg_hi:[1,0,0]
	v_pk_fma_f32 v[138:139], v[138:139], v[172:173], v[176:177]
	v_pk_fma_f32 v[140:141], v[140:141], v[174:175], v[178:179]
	v_pk_mul_f32 v[144:145], v[138:139], v[186:187]
	v_pk_fma_f32 v[144:145], v[140:141], v[188:189], v[144:145]
	v_add_f32 v146, v144, v145
	ds_read_b128 v[230:233], v5 offset:4608
	ds_read_b128 v[234:237], v5 offset:4864
	ds_read_b128 v[238:241], v5 offset:5120
	ds_read_b128 v[242:245], v5 offset:5376
	ds_read_b128 v[246:249], v5 offset:5632
	ds_read_b32 v250, v9 offset:4608
	v_add_f32_dpp v146, v146, v146 quad_perm:[1,0,3,2] row_mask:0xf bank_mask:0xf bound_ctrl:1
	v_pk_mul_f32 v[180:181], v[138:139], v[180:181]
	v_pk_fma_f32 v[180:181], v[140:141], v[182:183], v[180:181]
	v_add_f32_dpp v146, v146, v146 quad_perm:[2,3,0,1] row_mask:0xf bank_mask:0xf bound_ctrl:1
	v_add_f32 v148, v180, v181
	v_pk_mul_f32 v[198:199], v[198:199], v[206:207] op_sel_hi:[1,0]
	v_add_f32_dpp v146, v146, v146 row_half_mirror row_mask:0xf bank_mask:0xf bound_ctrl:1
	v_pk_mul_f32 v[200:201], v[200:201], v[206:207] op_sel_hi:[1,0]
	s_waitcnt lgkmcnt(6)
	v_add_f32_dpp v146, v146, v146 row_mirror row_mask:0xf bank_mask:0xf bound_ctrl:1
	v_pk_fma_f32 v[198:199], v[146:147], v[190:191], v[198:199] op_sel_hi:[0,1,1] neg_lo:[1,0,0] neg_hi:[1,0,0]
	v_pk_fma_f32 v[200:201], v[146:147], v[192:193], v[200:201] op_sel_hi:[0,1,1] neg_lo:[1,0,0] neg_hi:[1,0,0]
	v_pk_fma_f32 v[138:139], v[138:139], v[194:195], v[198:199]
	v_pk_fma_f32 v[140:141], v[140:141], v[196:197], v[200:201]
	v_pk_mul_f32 v[144:145], v[138:139], v[208:209]
	v_pk_fma_f32 v[144:145], v[140:141], v[210:211], v[144:145]
	v_add_f32 v146, v144, v145
	ds_read_b128 v[164:167], v5 offset:6144
	ds_read_b128 v[168:171], v5 offset:6400
	ds_read_b128 v[172:175], v5 offset:6656
	ds_read_b128 v[176:179], v5 offset:6912
	ds_read_b128 v[180:183], v5 offset:7168
	ds_read_b32 v184, v9 offset:6144
	v_add_f32_dpp v146, v146, v146 quad_perm:[1,0,3,2] row_mask:0xf bank_mask:0xf bound_ctrl:1
	v_pk_mul_f32 v[202:203], v[138:139], v[202:203]
	v_pk_fma_f32 v[202:203], v[140:141], v[204:205], v[202:203]
	v_add_f32_dpp v146, v146, v146 quad_perm:[2,3,0,1] row_mask:0xf bank_mask:0xf bound_ctrl:1
	v_add_f32 v149, v202, v203
	v_pk_mul_f32 v[220:221], v[220:221], v[228:229] op_sel_hi:[1,0]
	v_add_f32_dpp v146, v146, v146 row_half_mirror row_mask:0xf bank_mask:0xf bound_ctrl:1
	v_pk_mul_f32 v[222:223], v[222:223], v[228:229] op_sel_hi:[1,0]
	s_waitcnt lgkmcnt(6)
	v_add_f32_dpp v146, v146, v146 row_mirror row_mask:0xf bank_mask:0xf bound_ctrl:1
	v_pk_fma_f32 v[220:221], v[146:147], v[212:213], v[220:221] op_sel_hi:[0,1,1] neg_lo:[1,0,0] neg_hi:[1,0,0]
	v_pk_fma_f32 v[222:223], v[146:147], v[214:215], v[222:223] op_sel_hi:[0,1,1] neg_lo:[1,0,0] neg_hi:[1,0,0]
	v_pk_fma_f32 v[138:139], v[138:139], v[216:217], v[220:221]
	v_pk_fma_f32 v[140:141], v[140:141], v[218:219], v[222:223]
	v_pk_mul_f32 v[144:145], v[138:139], v[230:231]
	v_pk_fma_f32 v[144:145], v[140:141], v[232:233], v[144:145]
	v_add_f32 v146, v144, v145
	ds_read_b128 v[186:189], v5 offset:7680
	ds_read_b128 v[190:193], v5 offset:7936
	ds_read_b128 v[194:197], v5 offset:8192
	ds_read_b128 v[198:201], v5 offset:8448
	ds_read_b128 v[202:205], v5 offset:8704
	ds_read_b32 v206, v9 offset:7680
	v_add_f32_dpp v146, v146, v146 quad_perm:[1,0,3,2] row_mask:0xf bank_mask:0xf bound_ctrl:1
	v_pk_mul_f32 v[224:225], v[138:139], v[224:225]
	v_pk_fma_f32 v[224:225], v[140:141], v[226:227], v[224:225]
	v_add_f32_dpp v146, v146, v146 quad_perm:[2,3,0,1] row_mask:0xf bank_mask:0xf bound_ctrl:1
	v_add_f32 v150, v224, v225
	v_pk_mul_f32 v[242:243], v[242:243], v[250:251] op_sel_hi:[1,0]
	v_add_f32_dpp v146, v146, v146 row_half_mirror row_mask:0xf bank_mask:0xf bound_ctrl:1
	v_pk_mul_f32 v[244:245], v[244:245], v[250:251] op_sel_hi:[1,0]
	s_waitcnt lgkmcnt(6)
	v_add_f32_dpp v146, v146, v146 row_mirror row_mask:0xf bank_mask:0xf bound_ctrl:1
	v_pk_fma_f32 v[242:243], v[146:147], v[234:235], v[242:243] op_sel_hi:[0,1,1] neg_lo:[1,0,0] neg_hi:[1,0,0]
	v_pk_fma_f32 v[244:245], v[146:147], v[236:237], v[244:245] op_sel_hi:[0,1,1] neg_lo:[1,0,0] neg_hi:[1,0,0]
	v_pk_fma_f32 v[138:139], v[138:139], v[238:239], v[242:243]
	v_pk_fma_f32 v[140:141], v[140:141], v[240:241], v[244:245]
	v_pk_mul_f32 v[144:145], v[138:139], v[164:165]
	v_pk_fma_f32 v[144:145], v[140:141], v[166:167], v[144:145]
	v_add_f32 v146, v144, v145
	ds_read_b128 v[208:211], v5 offset:9216
	ds_read_b128 v[212:215], v5 offset:9472
	ds_read_b128 v[216:219], v5 offset:9728
	ds_read_b128 v[220:223], v5 offset:9984
	ds_read_b128 v[224:227], v5 offset:10240
	ds_read_b32 v228, v9 offset:9216
	v_add_f32_dpp v146, v146, v146 quad_perm:[1,0,3,2] row_mask:0xf bank_mask:0xf bound_ctrl:1
	v_pk_mul_f32 v[246:247], v[138:139], v[246:247]
	v_pk_fma_f32 v[246:247], v[140:141], v[248:249], v[246:247]
	v_add_f32_dpp v146, v146, v146 quad_perm:[2,3,0,1] row_mask:0xf bank_mask:0xf bound_ctrl:1
	v_add_f32 v151, v246, v247
	v_pk_mul_f32 v[176:177], v[176:177], v[184:185] op_sel_hi:[1,0]
	v_add_f32_dpp v146, v146, v146 row_half_mirror row_mask:0xf bank_mask:0xf bound_ctrl:1
	v_pk_mul_f32 v[178:179], v[178:179], v[184:185] op_sel_hi:[1,0]
	s_waitcnt lgkmcnt(6)
	v_add_f32_dpp v146, v146, v146 row_mirror row_mask:0xf bank_mask:0xf bound_ctrl:1
	v_pk_fma_f32 v[176:177], v[146:147], v[168:169], v[176:177] op_sel_hi:[0,1,1] neg_lo:[1,0,0] neg_hi:[1,0,0]
	v_pk_fma_f32 v[178:179], v[146:147], v[170:171], v[178:179] op_sel_hi:[0,1,1] neg_lo:[1,0,0] neg_hi:[1,0,0]
	v_pk_fma_f32 v[138:139], v[138:139], v[172:173], v[176:177]
	v_pk_fma_f32 v[140:141], v[140:141], v[174:175], v[178:179]
	v_pk_mul_f32 v[144:145], v[138:139], v[186:187]
	v_pk_fma_f32 v[144:145], v[140:141], v[188:189], v[144:145]
	v_add_f32 v146, v144, v145
	ds_read_b128 v[230:233], v5 offset:10752
	ds_read_b128 v[234:237], v5 offset:11008
	ds_read_b128 v[238:241], v5 offset:11264
	ds_read_b128 v[242:245], v5 offset:11520
	ds_read_b128 v[246:249], v5 offset:11776
	ds_read_b32 v250, v9 offset:10752
	v_add_f32_dpp v146, v146, v146 quad_perm:[1,0,3,2] row_mask:0xf bank_mask:0xf bound_ctrl:1
	v_pk_mul_f32 v[180:181], v[138:139], v[180:181]
	v_pk_fma_f32 v[180:181], v[140:141], v[182:183], v[180:181]
	v_add_f32_dpp v146, v146, v146 quad_perm:[2,3,0,1] row_mask:0xf bank_mask:0xf bound_ctrl:1
	v_add_f32 v152, v180, v181
	v_pk_mul_f32 v[198:199], v[198:199], v[206:207] op_sel_hi:[1,0]
	v_add_f32_dpp v146, v146, v146 row_half_mirror row_mask:0xf bank_mask:0xf bound_ctrl:1
	v_pk_mul_f32 v[200:201], v[200:201], v[206:207] op_sel_hi:[1,0]
	s_waitcnt lgkmcnt(6)
	v_add_f32_dpp v146, v146, v146 row_mirror row_mask:0xf bank_mask:0xf bound_ctrl:1
	v_pk_fma_f32 v[198:199], v[146:147], v[190:191], v[198:199] op_sel_hi:[0,1,1] neg_lo:[1,0,0] neg_hi:[1,0,0]
	v_pk_fma_f32 v[200:201], v[146:147], v[192:193], v[200:201] op_sel_hi:[0,1,1] neg_lo:[1,0,0] neg_hi:[1,0,0]
	v_pk_fma_f32 v[138:139], v[138:139], v[194:195], v[198:199]
	v_pk_fma_f32 v[140:141], v[140:141], v[196:197], v[200:201]
	v_pk_mul_f32 v[144:145], v[138:139], v[208:209]
	v_pk_fma_f32 v[144:145], v[140:141], v[210:211], v[144:145]
	v_add_f32 v146, v144, v145
	ds_read_b128 v[164:167], v5 offset:12288
	ds_read_b128 v[168:171], v5 offset:12544
	ds_read_b128 v[172:175], v5 offset:12800
	ds_read_b128 v[176:179], v5 offset:13056
	ds_read_b128 v[180:183], v5 offset:13312
	ds_read_b32 v184, v9 offset:12288
	v_add_f32_dpp v146, v146, v146 quad_perm:[1,0,3,2] row_mask:0xf bank_mask:0xf bound_ctrl:1
	v_pk_mul_f32 v[202:203], v[138:139], v[202:203]
	v_pk_fma_f32 v[202:203], v[140:141], v[204:205], v[202:203]
	v_add_f32_dpp v146, v146, v146 quad_perm:[2,3,0,1] row_mask:0xf bank_mask:0xf bound_ctrl:1
	v_add_f32 v153, v202, v203
	v_pk_mul_f32 v[220:221], v[220:221], v[228:229] op_sel_hi:[1,0]
	v_add_f32_dpp v146, v146, v146 row_half_mirror row_mask:0xf bank_mask:0xf bound_ctrl:1
	v_pk_mul_f32 v[222:223], v[222:223], v[228:229] op_sel_hi:[1,0]
	s_waitcnt lgkmcnt(6)
	v_add_f32_dpp v146, v146, v146 row_mirror row_mask:0xf bank_mask:0xf bound_ctrl:1
	v_pk_fma_f32 v[220:221], v[146:147], v[212:213], v[220:221] op_sel_hi:[0,1,1] neg_lo:[1,0,0] neg_hi:[1,0,0]
	v_pk_fma_f32 v[222:223], v[146:147], v[214:215], v[222:223] op_sel_hi:[0,1,1] neg_lo:[1,0,0] neg_hi:[1,0,0]
	v_pk_fma_f32 v[138:139], v[138:139], v[216:217], v[220:221]
	v_pk_fma_f32 v[140:141], v[140:141], v[218:219], v[222:223]
	v_pk_mul_f32 v[144:145], v[138:139], v[230:231]
	v_pk_fma_f32 v[144:145], v[140:141], v[232:233], v[144:145]
	v_add_f32 v146, v144, v145
	ds_read_b128 v[186:189], v5 offset:13824
	ds_read_b128 v[190:193], v5 offset:14080
	ds_read_b128 v[194:197], v5 offset:14336
	ds_read_b128 v[198:201], v5 offset:14592
	ds_read_b128 v[202:205], v5 offset:14848
	ds_read_b32 v206, v9 offset:13824
	v_add_f32_dpp v146, v146, v146 quad_perm:[1,0,3,2] row_mask:0xf bank_mask:0xf bound_ctrl:1
	v_pk_mul_f32 v[224:225], v[138:139], v[224:225]
	v_pk_fma_f32 v[224:225], v[140:141], v[226:227], v[224:225]
	v_add_f32_dpp v146, v146, v146 quad_perm:[2,3,0,1] row_mask:0xf bank_mask:0xf bound_ctrl:1
	v_add_f32 v154, v224, v225
	v_pk_mul_f32 v[242:243], v[242:243], v[250:251] op_sel_hi:[1,0]
	v_add_f32_dpp v146, v146, v146 row_half_mirror row_mask:0xf bank_mask:0xf bound_ctrl:1
	v_pk_mul_f32 v[244:245], v[244:245], v[250:251] op_sel_hi:[1,0]
	s_waitcnt lgkmcnt(6)
	v_add_f32_dpp v146, v146, v146 row_mirror row_mask:0xf bank_mask:0xf bound_ctrl:1
	v_pk_fma_f32 v[242:243], v[146:147], v[234:235], v[242:243] op_sel_hi:[0,1,1] neg_lo:[1,0,0] neg_hi:[1,0,0]
	v_pk_fma_f32 v[244:245], v[146:147], v[236:237], v[244:245] op_sel_hi:[0,1,1] neg_lo:[1,0,0] neg_hi:[1,0,0]
	v_pk_fma_f32 v[138:139], v[138:139], v[238:239], v[242:243]
	v_pk_fma_f32 v[140:141], v[140:141], v[240:241], v[244:245]
	v_pk_mul_f32 v[144:145], v[138:139], v[164:165]
	v_pk_fma_f32 v[144:145], v[140:141], v[166:167], v[144:145]
	v_add_f32 v146, v144, v145
	ds_read_b128 v[208:211], v5 offset:15360
	ds_read_b128 v[212:215], v5 offset:15616
	ds_read_b128 v[216:219], v5 offset:15872
	ds_read_b128 v[220:223], v5 offset:16128
	ds_read_b128 v[224:227], v5 offset:16384
	ds_read_b32 v228, v9 offset:15360
	v_add_f32_dpp v146, v146, v146 quad_perm:[1,0,3,2] row_mask:0xf bank_mask:0xf bound_ctrl:1
	v_pk_mul_f32 v[246:247], v[138:139], v[246:247]
	v_pk_fma_f32 v[246:247], v[140:141], v[248:249], v[246:247]
	v_add_f32_dpp v146, v146, v146 quad_perm:[2,3,0,1] row_mask:0xf bank_mask:0xf bound_ctrl:1
	v_add_f32 v155, v246, v247
	v_pk_mul_f32 v[176:177], v[176:177], v[184:185] op_sel_hi:[1,0]
	v_add_f32_dpp v146, v146, v146 row_half_mirror row_mask:0xf bank_mask:0xf bound_ctrl:1
	v_pk_mul_f32 v[178:179], v[178:179], v[184:185] op_sel_hi:[1,0]
	s_waitcnt lgkmcnt(6)
	v_add_f32_dpp v146, v146, v146 row_mirror row_mask:0xf bank_mask:0xf bound_ctrl:1
	v_pk_fma_f32 v[176:177], v[146:147], v[168:169], v[176:177] op_sel_hi:[0,1,1] neg_lo:[1,0,0] neg_hi:[1,0,0]
	v_pk_fma_f32 v[178:179], v[146:147], v[170:171], v[178:179] op_sel_hi:[0,1,1] neg_lo:[1,0,0] neg_hi:[1,0,0]
	v_pk_fma_f32 v[138:139], v[138:139], v[172:173], v[176:177]
	v_pk_fma_f32 v[140:141], v[140:141], v[174:175], v[178:179]
	v_pk_mul_f32 v[144:145], v[138:139], v[186:187]
	v_pk_fma_f32 v[144:145], v[140:141], v[188:189], v[144:145]
	v_add_f32 v146, v144, v145
	ds_read_b128 v[230:233], v5 offset:16896
	ds_read_b128 v[234:237], v5 offset:17152
	ds_read_b128 v[238:241], v5 offset:17408
	ds_read_b128 v[242:245], v5 offset:17664
	ds_read_b128 v[246:249], v5 offset:17920
	ds_read_b32 v250, v9 offset:16896
	v_add_f32_dpp v146, v146, v146 quad_perm:[1,0,3,2] row_mask:0xf bank_mask:0xf bound_ctrl:1
	v_pk_mul_f32 v[180:181], v[138:139], v[180:181]
	v_pk_fma_f32 v[180:181], v[140:141], v[182:183], v[180:181]
	v_add_f32_dpp v146, v146, v146 quad_perm:[2,3,0,1] row_mask:0xf bank_mask:0xf bound_ctrl:1
	v_add_f32 v156, v180, v181
	v_pk_mul_f32 v[198:199], v[198:199], v[206:207] op_sel_hi:[1,0]
	v_add_f32_dpp v146, v146, v146 row_half_mirror row_mask:0xf bank_mask:0xf bound_ctrl:1
	v_pk_mul_f32 v[200:201], v[200:201], v[206:207] op_sel_hi:[1,0]
	s_waitcnt lgkmcnt(6)
	v_add_f32_dpp v146, v146, v146 row_mirror row_mask:0xf bank_mask:0xf bound_ctrl:1
	v_pk_fma_f32 v[198:199], v[146:147], v[190:191], v[198:199] op_sel_hi:[0,1,1] neg_lo:[1,0,0] neg_hi:[1,0,0]
	v_pk_fma_f32 v[200:201], v[146:147], v[192:193], v[200:201] op_sel_hi:[0,1,1] neg_lo:[1,0,0] neg_hi:[1,0,0]
	v_pk_fma_f32 v[138:139], v[138:139], v[194:195], v[198:199]
	v_pk_fma_f32 v[140:141], v[140:141], v[196:197], v[200:201]
	v_pk_mul_f32 v[144:145], v[138:139], v[208:209]
	v_pk_fma_f32 v[144:145], v[140:141], v[210:211], v[144:145]
	v_add_f32 v146, v144, v145
	ds_read_b128 v[164:167], v5 offset:18432
	ds_read_b128 v[168:171], v5 offset:18688
	ds_read_b128 v[172:175], v5 offset:18944
	ds_read_b128 v[176:179], v5 offset:19200
	ds_read_b128 v[180:183], v5 offset:19456
	ds_read_b32 v184, v9 offset:18432
	v_add_f32_dpp v146, v146, v146 quad_perm:[1,0,3,2] row_mask:0xf bank_mask:0xf bound_ctrl:1
	v_pk_mul_f32 v[202:203], v[138:139], v[202:203]
	v_pk_fma_f32 v[202:203], v[140:141], v[204:205], v[202:203]
	v_add_f32_dpp v146, v146, v146 quad_perm:[2,3,0,1] row_mask:0xf bank_mask:0xf bound_ctrl:1
	v_add_f32 v157, v202, v203
	v_pk_mul_f32 v[220:221], v[220:221], v[228:229] op_sel_hi:[1,0]
	v_add_f32_dpp v146, v146, v146 row_half_mirror row_mask:0xf bank_mask:0xf bound_ctrl:1
	v_pk_mul_f32 v[222:223], v[222:223], v[228:229] op_sel_hi:[1,0]
	s_waitcnt lgkmcnt(6)
	v_add_f32_dpp v146, v146, v146 row_mirror row_mask:0xf bank_mask:0xf bound_ctrl:1
	v_pk_fma_f32 v[220:221], v[146:147], v[212:213], v[220:221] op_sel_hi:[0,1,1] neg_lo:[1,0,0] neg_hi:[1,0,0]
	v_pk_fma_f32 v[222:223], v[146:147], v[214:215], v[222:223] op_sel_hi:[0,1,1] neg_lo:[1,0,0] neg_hi:[1,0,0]
	v_pk_fma_f32 v[138:139], v[138:139], v[216:217], v[220:221]
	v_pk_fma_f32 v[140:141], v[140:141], v[218:219], v[222:223]
	v_pk_mul_f32 v[144:145], v[138:139], v[230:231]
	v_pk_fma_f32 v[144:145], v[140:141], v[232:233], v[144:145]
	v_add_f32 v146, v144, v145
	ds_read_b128 v[186:189], v5 offset:19968
	ds_read_b128 v[190:193], v5 offset:20224
	ds_read_b128 v[194:197], v5 offset:20480
	ds_read_b128 v[198:201], v5 offset:20736
	ds_read_b128 v[202:205], v5 offset:20992
	ds_read_b32 v206, v9 offset:19968
	v_add_f32_dpp v146, v146, v146 quad_perm:[1,0,3,2] row_mask:0xf bank_mask:0xf bound_ctrl:1
	v_pk_mul_f32 v[224:225], v[138:139], v[224:225]
	v_pk_fma_f32 v[224:225], v[140:141], v[226:227], v[224:225]
	v_add_f32_dpp v146, v146, v146 quad_perm:[2,3,0,1] row_mask:0xf bank_mask:0xf bound_ctrl:1
	v_add_f32 v158, v224, v225
	v_pk_mul_f32 v[242:243], v[242:243], v[250:251] op_sel_hi:[1,0]
	v_add_f32_dpp v146, v146, v146 row_half_mirror row_mask:0xf bank_mask:0xf bound_ctrl:1
	v_pk_mul_f32 v[244:245], v[244:245], v[250:251] op_sel_hi:[1,0]
	s_waitcnt lgkmcnt(6)
	v_add_f32_dpp v146, v146, v146 row_mirror row_mask:0xf bank_mask:0xf bound_ctrl:1
	v_pk_fma_f32 v[242:243], v[146:147], v[234:235], v[242:243] op_sel_hi:[0,1,1] neg_lo:[1,0,0] neg_hi:[1,0,0]
	v_pk_fma_f32 v[244:245], v[146:147], v[236:237], v[244:245] op_sel_hi:[0,1,1] neg_lo:[1,0,0] neg_hi:[1,0,0]
	v_pk_fma_f32 v[138:139], v[138:139], v[238:239], v[242:243]
	v_pk_fma_f32 v[140:141], v[140:141], v[240:241], v[244:245]
	v_pk_mul_f32 v[144:145], v[138:139], v[164:165]
	v_pk_fma_f32 v[144:145], v[140:141], v[166:167], v[144:145]
	v_add_f32 v146, v144, v145
	ds_read_b128 v[208:211], v5 offset:21504
	ds_read_b128 v[212:215], v5 offset:21760
	ds_read_b128 v[216:219], v5 offset:22016
	ds_read_b128 v[220:223], v5 offset:22272
	ds_read_b128 v[224:227], v5 offset:22528
	ds_read_b32 v228, v9 offset:21504
	v_add_f32_dpp v146, v146, v146 quad_perm:[1,0,3,2] row_mask:0xf bank_mask:0xf bound_ctrl:1
	v_pk_mul_f32 v[246:247], v[138:139], v[246:247]
	v_pk_fma_f32 v[246:247], v[140:141], v[248:249], v[246:247]
	v_add_f32_dpp v146, v146, v146 quad_perm:[2,3,0,1] row_mask:0xf bank_mask:0xf bound_ctrl:1
	v_add_f32 v159, v246, v247
	v_pk_mul_f32 v[176:177], v[176:177], v[184:185] op_sel_hi:[1,0]
	v_add_f32_dpp v146, v146, v146 row_half_mirror row_mask:0xf bank_mask:0xf bound_ctrl:1
	v_pk_mul_f32 v[178:179], v[178:179], v[184:185] op_sel_hi:[1,0]
	s_waitcnt lgkmcnt(6)
	v_add_f32_dpp v146, v146, v146 row_mirror row_mask:0xf bank_mask:0xf bound_ctrl:1
	v_pk_fma_f32 v[176:177], v[146:147], v[168:169], v[176:177] op_sel_hi:[0,1,1] neg_lo:[1,0,0] neg_hi:[1,0,0]
	v_pk_fma_f32 v[178:179], v[146:147], v[170:171], v[178:179] op_sel_hi:[0,1,1] neg_lo:[1,0,0] neg_hi:[1,0,0]
	v_pk_fma_f32 v[138:139], v[138:139], v[172:173], v[176:177]
	v_pk_fma_f32 v[140:141], v[140:141], v[174:175], v[178:179]
	v_pk_mul_f32 v[144:145], v[138:139], v[186:187]
	v_pk_fma_f32 v[144:145], v[140:141], v[188:189], v[144:145]
	v_add_f32 v146, v144, v145
	ds_read_b128 v[230:233], v5 offset:23040
	ds_read_b128 v[234:237], v5 offset:23296
	ds_read_b128 v[238:241], v5 offset:23552
	ds_read_b128 v[242:245], v5 offset:23808
	ds_read_b128 v[246:249], v5 offset:24064
	ds_read_b32 v250, v9 offset:23040
	v_add_f32_dpp v146, v146, v146 quad_perm:[1,0,3,2] row_mask:0xf bank_mask:0xf bound_ctrl:1
	v_pk_mul_f32 v[180:181], v[138:139], v[180:181]
	v_pk_fma_f32 v[180:181], v[140:141], v[182:183], v[180:181]
	v_add_f32_dpp v146, v146, v146 quad_perm:[2,3,0,1] row_mask:0xf bank_mask:0xf bound_ctrl:1
	v_add_f32 v160, v180, v181
	v_pk_mul_f32 v[198:199], v[198:199], v[206:207] op_sel_hi:[1,0]
	v_add_f32_dpp v146, v146, v146 row_half_mirror row_mask:0xf bank_mask:0xf bound_ctrl:1
	v_pk_mul_f32 v[200:201], v[200:201], v[206:207] op_sel_hi:[1,0]
	s_waitcnt lgkmcnt(6)
	v_add_f32_dpp v146, v146, v146 row_mirror row_mask:0xf bank_mask:0xf bound_ctrl:1
	v_pk_fma_f32 v[198:199], v[146:147], v[190:191], v[198:199] op_sel_hi:[0,1,1] neg_lo:[1,0,0] neg_hi:[1,0,0]
	v_pk_fma_f32 v[200:201], v[146:147], v[192:193], v[200:201] op_sel_hi:[0,1,1] neg_lo:[1,0,0] neg_hi:[1,0,0]
	v_pk_fma_f32 v[138:139], v[138:139], v[194:195], v[198:199]
	v_pk_fma_f32 v[140:141], v[140:141], v[196:197], v[200:201]
	v_pk_mul_f32 v[144:145], v[138:139], v[208:209]
	v_pk_fma_f32 v[144:145], v[140:141], v[210:211], v[144:145]
	v_add_f32 v146, v144, v145
	ds_read_b128 v[164:167], v5 offset:24576
	ds_read_b128 v[168:171], v5 offset:24832
	ds_read_b128 v[172:175], v5 offset:25088
	ds_read_b128 v[176:179], v5 offset:25344
	ds_read_b128 v[180:183], v5 offset:25600
	ds_read_b32 v184, v9 offset:24576
	v_add_f32_dpp v146, v146, v146 quad_perm:[1,0,3,2] row_mask:0xf bank_mask:0xf bound_ctrl:1
	v_pk_mul_f32 v[202:203], v[138:139], v[202:203]
	v_pk_fma_f32 v[202:203], v[140:141], v[204:205], v[202:203]
	v_add_f32_dpp v146, v146, v146 quad_perm:[2,3,0,1] row_mask:0xf bank_mask:0xf bound_ctrl:1
	v_add_f32 v161, v202, v203
	v_pk_mul_f32 v[220:221], v[220:221], v[228:229] op_sel_hi:[1,0]
	v_add_f32_dpp v146, v146, v146 row_half_mirror row_mask:0xf bank_mask:0xf bound_ctrl:1
	v_pk_mul_f32 v[222:223], v[222:223], v[228:229] op_sel_hi:[1,0]
	s_waitcnt lgkmcnt(6)
	v_add_f32_dpp v146, v146, v146 row_mirror row_mask:0xf bank_mask:0xf bound_ctrl:1
	v_pk_fma_f32 v[220:221], v[146:147], v[212:213], v[220:221] op_sel_hi:[0,1,1] neg_lo:[1,0,0] neg_hi:[1,0,0]
	v_pk_fma_f32 v[222:223], v[146:147], v[214:215], v[222:223] op_sel_hi:[0,1,1] neg_lo:[1,0,0] neg_hi:[1,0,0]
	v_pk_fma_f32 v[138:139], v[138:139], v[216:217], v[220:221]
	v_pk_fma_f32 v[140:141], v[140:141], v[218:219], v[222:223]
	v_pk_mul_f32 v[144:145], v[138:139], v[230:231]
	v_pk_fma_f32 v[144:145], v[140:141], v[232:233], v[144:145]
	v_add_f32 v146, v144, v145
	ds_read_b128 v[186:189], v5 offset:26112
	ds_read_b128 v[190:193], v5 offset:26368
	ds_read_b128 v[194:197], v5 offset:26624
	ds_read_b128 v[198:201], v5 offset:26880
	ds_read_b128 v[202:205], v5 offset:27136
	ds_read_b32 v206, v9 offset:26112
	v_add_f32_dpp v146, v146, v146 quad_perm:[1,0,3,2] row_mask:0xf bank_mask:0xf bound_ctrl:1
	v_pk_mul_f32 v[224:225], v[138:139], v[224:225]
	v_pk_fma_f32 v[224:225], v[140:141], v[226:227], v[224:225]
	v_add_f32_dpp v146, v146, v146 quad_perm:[2,3,0,1] row_mask:0xf bank_mask:0xf bound_ctrl:1
	v_add_f32 v162, v224, v225
	v_pk_mul_f32 v[242:243], v[242:243], v[250:251] op_sel_hi:[1,0]
	v_add_f32_dpp v146, v146, v146 row_half_mirror row_mask:0xf bank_mask:0xf bound_ctrl:1
	v_pk_mul_f32 v[244:245], v[244:245], v[250:251] op_sel_hi:[1,0]
	s_waitcnt lgkmcnt(6)
	v_add_f32_dpp v146, v146, v146 row_mirror row_mask:0xf bank_mask:0xf bound_ctrl:1
	v_pk_fma_f32 v[242:243], v[146:147], v[234:235], v[242:243] op_sel_hi:[0,1,1] neg_lo:[1,0,0] neg_hi:[1,0,0]
	v_pk_fma_f32 v[244:245], v[146:147], v[236:237], v[244:245] op_sel_hi:[0,1,1] neg_lo:[1,0,0] neg_hi:[1,0,0]
	v_pk_fma_f32 v[138:139], v[138:139], v[238:239], v[242:243]
	v_pk_fma_f32 v[140:141], v[140:141], v[240:241], v[244:245]
	v_pk_mul_f32 v[144:145], v[138:139], v[164:165]
	v_pk_fma_f32 v[144:145], v[140:141], v[166:167], v[144:145]
	v_add_f32 v146, v144, v145
	ds_read_b128 v[208:211], v5 offset:27648
	ds_read_b128 v[212:215], v5 offset:27904
	ds_read_b128 v[216:219], v5 offset:28160
	ds_read_b128 v[220:223], v5 offset:28416
	ds_read_b128 v[224:227], v5 offset:28672
	ds_read_b32 v228, v9 offset:27648
	v_add_f32_dpp v146, v146, v146 quad_perm:[1,0,3,2] row_mask:0xf bank_mask:0xf bound_ctrl:1
	v_pk_mul_f32 v[246:247], v[138:139], v[246:247]
	v_pk_fma_f32 v[246:247], v[140:141], v[248:249], v[246:247]
	v_add_f32_dpp v146, v146, v146 quad_perm:[2,3,0,1] row_mask:0xf bank_mask:0xf bound_ctrl:1
	v_add_f32 v163, v246, v247
	v_pk_mul_f32 v[176:177], v[176:177], v[184:185] op_sel_hi:[1,0]
	v_add_f32_dpp v146, v146, v146 row_half_mirror row_mask:0xf bank_mask:0xf bound_ctrl:1
	v_pk_mul_f32 v[178:179], v[178:179], v[184:185] op_sel_hi:[1,0]
	s_waitcnt lgkmcnt(6)
	v_add_f32_dpp v146, v146, v146 row_mirror row_mask:0xf bank_mask:0xf bound_ctrl:1
	v_pk_fma_f32 v[176:177], v[146:147], v[168:169], v[176:177] op_sel_hi:[0,1,1] neg_lo:[1,0,0] neg_hi:[1,0,0]
	v_pk_fma_f32 v[178:179], v[146:147], v[170:171], v[178:179] op_sel_hi:[0,1,1] neg_lo:[1,0,0] neg_hi:[1,0,0]
	v_pk_fma_f32 v[138:139], v[138:139], v[172:173], v[176:177]
	v_pk_fma_f32 v[140:141], v[140:141], v[174:175], v[178:179]
	v_pk_mul_f32 v[144:145], v[138:139], v[186:187]
	v_pk_fma_f32 v[144:145], v[140:141], v[188:189], v[144:145]
	v_add_f32 v146, v144, v145
	v_and_b32 v244, 8, v3
	v_cmp_ne_u32 vcc, 0, v244
	v_cndmask_b32 v244, v156, v148, vcc
	v_cndmask_b32 v245, v157, v149, vcc
	v_cndmask_b32 v246, v158, v150, vcc
	v_cndmask_b32 v247, v159, v151, vcc
	v_cndmask_b32 v230, v148, v156, vcc
	v_cndmask_b32 v231, v149, v157, vcc
	v_cndmask_b32 v232, v150, v158, vcc
	v_cndmask_b32 v233, v151, v159, vcc
	v_add_f32_dpp v230, v244, v230 row_mirror row_mask:0xf bank_mask:0xf bound_ctrl:1
	v_add_f32_dpp v231, v245, v231 row_mirror row_mask:0xf bank_mask:0xf bound_ctrl:1
	v_add_f32_dpp v232, v246, v232 row_mirror row_mask:0xf bank_mask:0xf bound_ctrl:1
	v_add_f32_dpp v233, v247, v233 row_mirror row_mask:0xf bank_mask:0xf bound_ctrl:1
	v_cndmask_b32 v244, v160, v152, vcc
	v_cndmask_b32 v245, v161, v153, vcc
	v_cndmask_b32 v246, v162, v154, vcc
	v_cndmask_b32 v247, v163, v155, vcc
	v_cndmask_b32 v234, v152, v160, vcc
	v_cndmask_b32 v235, v153, v161, vcc
	v_cndmask_b32 v236, v154, v162, vcc
	v_cndmask_b32 v237, v155, v163, vcc
	v_add_f32_dpp v234, v244, v234 row_mirror row_mask:0xf bank_mask:0xf bound_ctrl:1
	v_add_f32_dpp v235, v245, v235 row_mirror row_mask:0xf bank_mask:0xf bound_ctrl:1
	v_add_f32_dpp v236, v246, v236 row_mirror row_mask:0xf bank_mask:0xf bound_ctrl:1
	v_add_f32_dpp v237, v247, v237 row_mirror row_mask:0xf bank_mask:0xf bound_ctrl:1
	v_and_b32 v244, 4, v3
	v_cmp_ne_u32 vcc, 0, v244
	v_cndmask_b32 v244, v234, v230, vcc
	v_cndmask_b32 v245, v235, v231, vcc
	v_cndmask_b32 v246, v236, v232, vcc
	v_cndmask_b32 v247, v237, v233, vcc
	v_cndmask_b32 v238, v230, v234, vcc
	v_cndmask_b32 v239, v231, v235, vcc
	v_cndmask_b32 v240, v232, v236, vcc
	v_cndmask_b32 v241, v233, v237, vcc
	v_add_f32_dpp v238, v244, v238 row_half_mirror row_mask:0xf bank_mask:0xf bound_ctrl:1
	v_add_f32_dpp v239, v245, v239 row_half_mirror row_mask:0xf bank_mask:0xf bound_ctrl:1
	v_add_f32_dpp v240, v246, v240 row_half_mirror row_mask:0xf bank_mask:0xf bound_ctrl:1
	v_add_f32_dpp v241, v247, v241 row_half_mirror row_mask:0xf bank_mask:0xf bound_ctrl:1
	v_and_b32 v244, 2, v3
	v_cmp_ne_u32 vcc, 0, v244
	v_cndmask_b32 v244, v240, v238, vcc
	v_cndmask_b32 v245, v241, v239, vcc
	v_cndmask_b32 v242, v238, v240, vcc
	v_cndmask_b32 v243, v239, v241, vcc
	v_add_f32_dpp v242, v244, v242 quad_perm:[2,3,0,1] row_mask:0xf bank_mask:0xf bound_ctrl:1
	v_add_f32_dpp v243, v245, v243 quad_perm:[2,3,0,1] row_mask:0xf bank_mask:0xf bound_ctrl:1
	v_and_b32 v244, 1, v3
	v_cmp_ne_u32 vcc, 0, v244
	v_cndmask_b32 v244, v243, v242, vcc
	v_cndmask_b32 v245, v242, v243, vcc
	s_nop 0
	v_add_f32_dpp v18, v244, v245 quad_perm:[1,0,3,2] row_mask:0xf bank_mask:0xf bound_ctrl:1
	ds_read_b128 v[230:233], v5 offset:29184
	ds_read_b128 v[234:237], v5 offset:29440
	ds_read_b128 v[238:241], v5 offset:29696
	ds_read_b128 v[242:245], v5 offset:29952
	ds_read_b128 v[246:249], v5 offset:30208
	ds_read_b32 v250, v9 offset:29184
	v_add_f32_dpp v146, v146, v146 quad_perm:[1,0,3,2] row_mask:0xf bank_mask:0xf bound_ctrl:1
	v_pk_mul_f32 v[180:181], v[138:139], v[180:181]
	v_pk_fma_f32 v[180:181], v[140:141], v[182:183], v[180:181]
	v_add_f32_dpp v146, v146, v146 quad_perm:[2,3,0,1] row_mask:0xf bank_mask:0xf bound_ctrl:1
	v_add_f32 v148, v180, v181
	v_pk_mul_f32 v[198:199], v[198:199], v[206:207] op_sel_hi:[1,0]
	v_add_f32_dpp v146, v146, v146 row_half_mirror row_mask:0xf bank_mask:0xf bound_ctrl:1
	v_pk_mul_f32 v[200:201], v[200:201], v[206:207] op_sel_hi:[1,0]
	s_waitcnt lgkmcnt(6)
	v_add_f32_dpp v146, v146, v146 row_mirror row_mask:0xf bank_mask:0xf bound_ctrl:1
	v_pk_fma_f32 v[198:199], v[146:147], v[190:191], v[198:199] op_sel_hi:[0,1,1] neg_lo:[1,0,0] neg_hi:[1,0,0]
	v_pk_fma_f32 v[200:201], v[146:147], v[192:193], v[200:201] op_sel_hi:[0,1,1] neg_lo:[1,0,0] neg_hi:[1,0,0]
	v_pk_fma_f32 v[138:139], v[138:139], v[194:195], v[198:199]
	v_pk_fma_f32 v[140:141], v[140:141], v[196:197], v[200:201]
	v_pk_mul_f32 v[144:145], v[138:139], v[208:209]
	v_pk_fma_f32 v[144:145], v[140:141], v[210:211], v[144:145]
	v_add_f32 v146, v144, v145
	ds_read_b128 v[164:167], v5 offset:30720
	ds_read_b128 v[168:171], v5 offset:30976
	ds_read_b128 v[172:175], v5 offset:31232
	ds_read_b128 v[176:179], v5 offset:31488
	ds_read_b128 v[180:183], v5 offset:31744
	ds_read_b32 v184, v9 offset:30720
	v_add_f32_dpp v146, v146, v146 quad_perm:[1,0,3,2] row_mask:0xf bank_mask:0xf bound_ctrl:1
	v_pk_mul_f32 v[202:203], v[138:139], v[202:203]
	v_pk_fma_f32 v[202:203], v[140:141], v[204:205], v[202:203]
	v_add_f32_dpp v146, v146, v146 quad_perm:[2,3,0,1] row_mask:0xf bank_mask:0xf bound_ctrl:1
	v_add_f32 v149, v202, v203
	v_pk_mul_f32 v[220:221], v[220:221], v[228:229] op_sel_hi:[1,0]
	v_add_f32_dpp v146, v146, v146 row_half_mirror row_mask:0xf bank_mask:0xf bound_ctrl:1
	v_pk_mul_f32 v[222:223], v[222:223], v[228:229] op_sel_hi:[1,0]
	s_waitcnt lgkmcnt(6)
	v_add_f32_dpp v146, v146, v146 row_mirror row_mask:0xf bank_mask:0xf bound_ctrl:1
	v_pk_fma_f32 v[220:221], v[146:147], v[212:213], v[220:221] op_sel_hi:[0,1,1] neg_lo:[1,0,0] neg_hi:[1,0,0]
	v_pk_fma_f32 v[222:223], v[146:147], v[214:215], v[222:223] op_sel_hi:[0,1,1] neg_lo:[1,0,0] neg_hi:[1,0,0]
	v_pk_fma_f32 v[138:139], v[138:139], v[216:217], v[220:221]
	v_pk_fma_f32 v[140:141], v[140:141], v[218:219], v[222:223]
	v_pk_mul_f32 v[144:145], v[138:139], v[230:231]
	v_pk_fma_f32 v[144:145], v[140:141], v[232:233], v[144:145]
	v_add_f32 v146, v144, v145
	ds_read_b128 v[186:189], v5 offset:32256
	ds_read_b128 v[190:193], v5 offset:32512
	ds_read_b128 v[194:197], v5 offset:32768
	ds_read_b128 v[198:201], v5 offset:33024
	ds_read_b128 v[202:205], v5 offset:33280
	ds_read_b32 v206, v9 offset:32256
	v_add_f32_dpp v146, v146, v146 quad_perm:[1,0,3,2] row_mask:0xf bank_mask:0xf bound_ctrl:1
	v_pk_mul_f32 v[224:225], v[138:139], v[224:225]
	v_pk_fma_f32 v[224:225], v[140:141], v[226:227], v[224:225]
	v_add_f32_dpp v146, v146, v146 quad_perm:[2,3,0,1] row_mask:0xf bank_mask:0xf bound_ctrl:1
	v_add_f32 v150, v224, v225
	v_pk_mul_f32 v[242:243], v[242:243], v[250:251] op_sel_hi:[1,0]
	v_add_f32_dpp v146, v146, v146 row_half_mirror row_mask:0xf bank_mask:0xf bound_ctrl:1
	v_pk_mul_f32 v[244:245], v[244:245], v[250:251] op_sel_hi:[1,0]
	s_waitcnt lgkmcnt(6)
	v_add_f32_dpp v146, v146, v146 row_mirror row_mask:0xf bank_mask:0xf bound_ctrl:1
	v_pk_fma_f32 v[242:243], v[146:147], v[234:235], v[242:243] op_sel_hi:[0,1,1] neg_lo:[1,0,0] neg_hi:[1,0,0]
	v_pk_fma_f32 v[244:245], v[146:147], v[236:237], v[244:245] op_sel_hi:[0,1,1] neg_lo:[1,0,0] neg_hi:[1,0,0]
	v_pk_fma_f32 v[138:139], v[138:139], v[238:239], v[242:243]
	v_pk_fma_f32 v[140:141], v[140:141], v[240:241], v[244:245]
	v_pk_mul_f32 v[144:145], v[138:139], v[164:165]
	v_pk_fma_f32 v[144:145], v[140:141], v[166:167], v[144:145]
	v_add_f32 v146, v144, v145
	ds_read_b128 v[208:211], v5 offset:33792
	ds_read_b128 v[212:215], v5 offset:34048
	ds_read_b128 v[216:219], v5 offset:34304
	ds_read_b128 v[220:223], v5 offset:34560
	ds_read_b128 v[224:227], v5 offset:34816
	ds_read_b32 v228, v9 offset:33792
	v_add_f32_dpp v146, v146, v146 quad_perm:[1,0,3,2] row_mask:0xf bank_mask:0xf bound_ctrl:1
	v_pk_mul_f32 v[246:247], v[138:139], v[246:247]
	v_pk_fma_f32 v[246:247], v[140:141], v[248:249], v[246:247]
	v_add_f32_dpp v146, v146, v146 quad_perm:[2,3,0,1] row_mask:0xf bank_mask:0xf bound_ctrl:1
	v_add_f32 v151, v246, v247
	v_pk_mul_f32 v[176:177], v[176:177], v[184:185] op_sel_hi:[1,0]
	v_add_f32_dpp v146, v146, v146 row_half_mirror row_mask:0xf bank_mask:0xf bound_ctrl:1
	v_pk_mul_f32 v[178:179], v[178:179], v[184:185] op_sel_hi:[1,0]
	s_waitcnt lgkmcnt(6)
	v_add_f32_dpp v146, v146, v146 row_mirror row_mask:0xf bank_mask:0xf bound_ctrl:1
	v_pk_fma_f32 v[176:177], v[146:147], v[168:169], v[176:177] op_sel_hi:[0,1,1] neg_lo:[1,0,0] neg_hi:[1,0,0]
	v_pk_fma_f32 v[178:179], v[146:147], v[170:171], v[178:179] op_sel_hi:[0,1,1] neg_lo:[1,0,0] neg_hi:[1,0,0]
	v_pk_fma_f32 v[138:139], v[138:139], v[172:173], v[176:177]
	v_pk_fma_f32 v[140:141], v[140:141], v[174:175], v[178:179]
	v_pk_mul_f32 v[144:145], v[138:139], v[186:187]
	v_pk_fma_f32 v[144:145], v[140:141], v[188:189], v[144:145]
	v_add_f32 v146, v144, v145
	ds_read_b128 v[230:233], v5 offset:35328
	ds_read_b128 v[234:237], v5 offset:35584
	ds_read_b128 v[238:241], v5 offset:35840
	ds_read_b128 v[242:245], v5 offset:36096
	ds_read_b128 v[246:249], v5 offset:36352
	ds_read_b32 v250, v9 offset:35328
	v_add_f32_dpp v146, v146, v146 quad_perm:[1,0,3,2] row_mask:0xf bank_mask:0xf bound_ctrl:1
	v_pk_mul_f32 v[180:181], v[138:139], v[180:181]
	v_pk_fma_f32 v[180:181], v[140:141], v[182:183], v[180:181]
	v_add_f32_dpp v146, v146, v146 quad_perm:[2,3,0,1] row_mask:0xf bank_mask:0xf bound_ctrl:1
	v_add_f32 v152, v180, v181
	v_pk_mul_f32 v[198:199], v[198:199], v[206:207] op_sel_hi:[1,0]
	v_add_f32_dpp v146, v146, v146 row_half_mirror row_mask:0xf bank_mask:0xf bound_ctrl:1
	v_pk_mul_f32 v[200:201], v[200:201], v[206:207] op_sel_hi:[1,0]
	s_waitcnt lgkmcnt(6)
	v_add_f32_dpp v146, v146, v146 row_mirror row_mask:0xf bank_mask:0xf bound_ctrl:1
	v_pk_fma_f32 v[198:199], v[146:147], v[190:191], v[198:199] op_sel_hi:[0,1,1] neg_lo:[1,0,0] neg_hi:[1,0,0]
	v_pk_fma_f32 v[200:201], v[146:147], v[192:193], v[200:201] op_sel_hi:[0,1,1] neg_lo:[1,0,0] neg_hi:[1,0,0]
	v_pk_fma_f32 v[138:139], v[138:139], v[194:195], v[198:199]
	v_pk_fma_f32 v[140:141], v[140:141], v[196:197], v[200:201]
	v_pk_mul_f32 v[144:145], v[138:139], v[208:209]
	v_pk_fma_f32 v[144:145], v[140:141], v[210:211], v[144:145]
	v_add_f32 v146, v144, v145
	ds_read_b128 v[164:167], v5 offset:36864
	ds_read_b128 v[168:171], v5 offset:37120
	ds_read_b128 v[172:175], v5 offset:37376
	ds_read_b128 v[176:179], v5 offset:37632
	ds_read_b128 v[180:183], v5 offset:37888
	ds_read_b32 v184, v9 offset:36864
	v_add_f32_dpp v146, v146, v146 quad_perm:[1,0,3,2] row_mask:0xf bank_mask:0xf bound_ctrl:1
	v_pk_mul_f32 v[202:203], v[138:139], v[202:203]
	v_pk_fma_f32 v[202:203], v[140:141], v[204:205], v[202:203]
	v_add_f32_dpp v146, v146, v146 quad_perm:[2,3,0,1] row_mask:0xf bank_mask:0xf bound_ctrl:1
	v_add_f32 v153, v202, v203
	v_pk_mul_f32 v[220:221], v[220:221], v[228:229] op_sel_hi:[1,0]
	v_add_f32_dpp v146, v146, v146 row_half_mirror row_mask:0xf bank_mask:0xf bound_ctrl:1
	v_pk_mul_f32 v[222:223], v[222:223], v[228:229] op_sel_hi:[1,0]
	s_waitcnt lgkmcnt(6)
	v_add_f32_dpp v146, v146, v146 row_mirror row_mask:0xf bank_mask:0xf bound_ctrl:1
	v_pk_fma_f32 v[220:221], v[146:147], v[212:213], v[220:221] op_sel_hi:[0,1,1] neg_lo:[1,0,0] neg_hi:[1,0,0]
	v_pk_fma_f32 v[222:223], v[146:147], v[214:215], v[222:223] op_sel_hi:[0,1,1] neg_lo:[1,0,0] neg_hi:[1,0,0]
	v_pk_fma_f32 v[138:139], v[138:139], v[216:217], v[220:221]
	v_pk_fma_f32 v[140:141], v[140:141], v[218:219], v[222:223]
	v_pk_mul_f32 v[144:145], v[138:139], v[230:231]
	v_pk_fma_f32 v[144:145], v[140:141], v[232:233], v[144:145]
	v_add_f32 v146, v144, v145
	ds_read_b128 v[186:189], v5 offset:38400
	ds_read_b128 v[190:193], v5 offset:38656
	ds_read_b128 v[194:197], v5 offset:38912
	ds_read_b128 v[198:201], v5 offset:39168
	ds_read_b128 v[202:205], v5 offset:39424
	ds_read_b32 v206, v9 offset:38400
	v_add_f32_dpp v146, v146, v146 quad_perm:[1,0,3,2] row_mask:0xf bank_mask:0xf bound_ctrl:1
	v_pk_mul_f32 v[224:225], v[138:139], v[224:225]
	v_pk_fma_f32 v[224:225], v[140:141], v[226:227], v[224:225]
	v_add_f32_dpp v146, v146, v146 quad_perm:[2,3,0,1] row_mask:0xf bank_mask:0xf bound_ctrl:1
	v_add_f32 v154, v224, v225
	v_pk_mul_f32 v[242:243], v[242:243], v[250:251] op_sel_hi:[1,0]
	v_add_f32_dpp v146, v146, v146 row_half_mirror row_mask:0xf bank_mask:0xf bound_ctrl:1
	v_pk_mul_f32 v[244:245], v[244:245], v[250:251] op_sel_hi:[1,0]
	s_waitcnt lgkmcnt(6)
	v_add_f32_dpp v146, v146, v146 row_mirror row_mask:0xf bank_mask:0xf bound_ctrl:1
	v_pk_fma_f32 v[242:243], v[146:147], v[234:235], v[242:243] op_sel_hi:[0,1,1] neg_lo:[1,0,0] neg_hi:[1,0,0]
	v_pk_fma_f32 v[244:245], v[146:147], v[236:237], v[244:245] op_sel_hi:[0,1,1] neg_lo:[1,0,0] neg_hi:[1,0,0]
	v_pk_fma_f32 v[138:139], v[138:139], v[238:239], v[242:243]
	v_pk_fma_f32 v[140:141], v[140:141], v[240:241], v[244:245]
	v_pk_mul_f32 v[144:145], v[138:139], v[164:165]
	v_pk_fma_f32 v[144:145], v[140:141], v[166:167], v[144:145]
	v_add_f32 v146, v144, v145
	ds_read_b128 v[208:211], v5 offset:39936
	ds_read_b128 v[212:215], v5 offset:40192
	ds_read_b128 v[216:219], v5 offset:40448
	ds_read_b128 v[220:223], v5 offset:40704
	ds_read_b128 v[224:227], v5 offset:40960
	ds_read_b32 v228, v9 offset:39936
	v_add_f32_dpp v146, v146, v146 quad_perm:[1,0,3,2] row_mask:0xf bank_mask:0xf bound_ctrl:1
	v_pk_mul_f32 v[246:247], v[138:139], v[246:247]
	v_pk_fma_f32 v[246:247], v[140:141], v[248:249], v[246:247]
	v_add_f32_dpp v146, v146, v146 quad_perm:[2,3,0,1] row_mask:0xf bank_mask:0xf bound_ctrl:1
	v_add_f32 v155, v246, v247
	v_pk_mul_f32 v[176:177], v[176:177], v[184:185] op_sel_hi:[1,0]
	v_add_f32_dpp v146, v146, v146 row_half_mirror row_mask:0xf bank_mask:0xf bound_ctrl:1
	v_pk_mul_f32 v[178:179], v[178:179], v[184:185] op_sel_hi:[1,0]
	s_waitcnt lgkmcnt(6)
	v_add_f32_dpp v146, v146, v146 row_mirror row_mask:0xf bank_mask:0xf bound_ctrl:1
	v_pk_fma_f32 v[176:177], v[146:147], v[168:169], v[176:177] op_sel_hi:[0,1,1] neg_lo:[1,0,0] neg_hi:[1,0,0]
	v_pk_fma_f32 v[178:179], v[146:147], v[170:171], v[178:179] op_sel_hi:[0,1,1] neg_lo:[1,0,0] neg_hi:[1,0,0]
	v_pk_fma_f32 v[138:139], v[138:139], v[172:173], v[176:177]
	v_pk_fma_f32 v[140:141], v[140:141], v[174:175], v[178:179]
	v_pk_mul_f32 v[144:145], v[138:139], v[186:187]
	v_pk_fma_f32 v[144:145], v[140:141], v[188:189], v[144:145]
	v_add_f32 v146, v144, v145
	ds_read_b128 v[230:233], v5 offset:41472
	ds_read_b128 v[234:237], v5 offset:41728
	ds_read_b128 v[238:241], v5 offset:41984
	ds_read_b128 v[242:245], v5 offset:42240
	ds_read_b128 v[246:249], v5 offset:42496
	ds_read_b32 v250, v9 offset:41472
	v_add_f32_dpp v146, v146, v146 quad_perm:[1,0,3,2] row_mask:0xf bank_mask:0xf bound_ctrl:1
	v_pk_mul_f32 v[180:181], v[138:139], v[180:181]
	v_pk_fma_f32 v[180:181], v[140:141], v[182:183], v[180:181]
	v_add_f32_dpp v146, v146, v146 quad_perm:[2,3,0,1] row_mask:0xf bank_mask:0xf bound_ctrl:1
	v_add_f32 v156, v180, v181
	v_pk_mul_f32 v[198:199], v[198:199], v[206:207] op_sel_hi:[1,0]
	v_add_f32_dpp v146, v146, v146 row_half_mirror row_mask:0xf bank_mask:0xf bound_ctrl:1
	v_pk_mul_f32 v[200:201], v[200:201], v[206:207] op_sel_hi:[1,0]
	s_waitcnt lgkmcnt(6)
	v_add_f32_dpp v146, v146, v146 row_mirror row_mask:0xf bank_mask:0xf bound_ctrl:1
	v_pk_fma_f32 v[198:199], v[146:147], v[190:191], v[198:199] op_sel_hi:[0,1,1] neg_lo:[1,0,0] neg_hi:[1,0,0]
	v_pk_fma_f32 v[200:201], v[146:147], v[192:193], v[200:201] op_sel_hi:[0,1,1] neg_lo:[1,0,0] neg_hi:[1,0,0]
	v_pk_fma_f32 v[138:139], v[138:139], v[194:195], v[198:199]
	v_pk_fma_f32 v[140:141], v[140:141], v[196:197], v[200:201]
	v_pk_mul_f32 v[144:145], v[138:139], v[208:209]
	v_pk_fma_f32 v[144:145], v[140:141], v[210:211], v[144:145]
	v_add_f32 v146, v144, v145
	ds_read_b128 v[164:167], v5 offset:43008
	ds_read_b128 v[168:171], v5 offset:43264
	ds_read_b128 v[172:175], v5 offset:43520
	ds_read_b128 v[176:179], v5 offset:43776
	ds_read_b128 v[180:183], v5 offset:44032
	ds_read_b32 v184, v9 offset:43008
	v_add_f32_dpp v146, v146, v146 quad_perm:[1,0,3,2] row_mask:0xf bank_mask:0xf bound_ctrl:1
	v_pk_mul_f32 v[202:203], v[138:139], v[202:203]
	v_pk_fma_f32 v[202:203], v[140:141], v[204:205], v[202:203]
	v_add_f32_dpp v146, v146, v146 quad_perm:[2,3,0,1] row_mask:0xf bank_mask:0xf bound_ctrl:1
	v_add_f32 v157, v202, v203
	v_pk_mul_f32 v[220:221], v[220:221], v[228:229] op_sel_hi:[1,0]
	v_add_f32_dpp v146, v146, v146 row_half_mirror row_mask:0xf bank_mask:0xf bound_ctrl:1
	v_pk_mul_f32 v[222:223], v[222:223], v[228:229] op_sel_hi:[1,0]
	s_waitcnt lgkmcnt(6)
	v_add_f32_dpp v146, v146, v146 row_mirror row_mask:0xf bank_mask:0xf bound_ctrl:1
	v_pk_fma_f32 v[220:221], v[146:147], v[212:213], v[220:221] op_sel_hi:[0,1,1] neg_lo:[1,0,0] neg_hi:[1,0,0]
	v_pk_fma_f32 v[222:223], v[146:147], v[214:215], v[222:223] op_sel_hi:[0,1,1] neg_lo:[1,0,0] neg_hi:[1,0,0]
	v_pk_fma_f32 v[138:139], v[138:139], v[216:217], v[220:221]
	v_pk_fma_f32 v[140:141], v[140:141], v[218:219], v[222:223]
	v_pk_mul_f32 v[144:145], v[138:139], v[230:231]
	v_pk_fma_f32 v[144:145], v[140:141], v[232:233], v[144:145]
	v_add_f32 v146, v144, v145
	ds_read_b128 v[186:189], v5 offset:44544
	ds_read_b128 v[190:193], v5 offset:44800
	ds_read_b128 v[194:197], v5 offset:45056
	ds_read_b128 v[198:201], v5 offset:45312
	ds_read_b128 v[202:205], v5 offset:45568
	ds_read_b32 v206, v9 offset:44544
	v_add_f32_dpp v146, v146, v146 quad_perm:[1,0,3,2] row_mask:0xf bank_mask:0xf bound_ctrl:1
	v_pk_mul_f32 v[224:225], v[138:139], v[224:225]
	v_pk_fma_f32 v[224:225], v[140:141], v[226:227], v[224:225]
	v_add_f32_dpp v146, v146, v146 quad_perm:[2,3,0,1] row_mask:0xf bank_mask:0xf bound_ctrl:1
	v_add_f32 v158, v224, v225
	v_pk_mul_f32 v[242:243], v[242:243], v[250:251] op_sel_hi:[1,0]
	v_add_f32_dpp v146, v146, v146 row_half_mirror row_mask:0xf bank_mask:0xf bound_ctrl:1
	v_pk_mul_f32 v[244:245], v[244:245], v[250:251] op_sel_hi:[1,0]
	s_waitcnt lgkmcnt(6)
	v_add_f32_dpp v146, v146, v146 row_mirror row_mask:0xf bank_mask:0xf bound_ctrl:1
	v_pk_fma_f32 v[242:243], v[146:147], v[234:235], v[242:243] op_sel_hi:[0,1,1] neg_lo:[1,0,0] neg_hi:[1,0,0]
	v_pk_fma_f32 v[244:245], v[146:147], v[236:237], v[244:245] op_sel_hi:[0,1,1] neg_lo:[1,0,0] neg_hi:[1,0,0]
	v_pk_fma_f32 v[138:139], v[138:139], v[238:239], v[242:243]
	v_pk_fma_f32 v[140:141], v[140:141], v[240:241], v[244:245]
	v_pk_mul_f32 v[144:145], v[138:139], v[164:165]
	v_pk_fma_f32 v[144:145], v[140:141], v[166:167], v[144:145]
	v_add_f32 v146, v144, v145
	ds_read_b128 v[208:211], v5 offset:46080
	ds_read_b128 v[212:215], v5 offset:46336
	ds_read_b128 v[216:219], v5 offset:46592
	ds_read_b128 v[220:223], v5 offset:46848
	ds_read_b128 v[224:227], v5 offset:47104
	ds_read_b32 v228, v9 offset:46080
	v_add_f32_dpp v146, v146, v146 quad_perm:[1,0,3,2] row_mask:0xf bank_mask:0xf bound_ctrl:1
	v_pk_mul_f32 v[246:247], v[138:139], v[246:247]
	v_pk_fma_f32 v[246:247], v[140:141], v[248:249], v[246:247]
	v_add_f32_dpp v146, v146, v146 quad_perm:[2,3,0,1] row_mask:0xf bank_mask:0xf bound_ctrl:1
	v_add_f32 v159, v246, v247
	v_pk_mul_f32 v[176:177], v[176:177], v[184:185] op_sel_hi:[1,0]
	v_add_f32_dpp v146, v146, v146 row_half_mirror row_mask:0xf bank_mask:0xf bound_ctrl:1
	v_pk_mul_f32 v[178:179], v[178:179], v[184:185] op_sel_hi:[1,0]
	s_waitcnt lgkmcnt(6)
	v_add_f32_dpp v146, v146, v146 row_mirror row_mask:0xf bank_mask:0xf bound_ctrl:1
	v_pk_fma_f32 v[176:177], v[146:147], v[168:169], v[176:177] op_sel_hi:[0,1,1] neg_lo:[1,0,0] neg_hi:[1,0,0]
	v_pk_fma_f32 v[178:179], v[146:147], v[170:171], v[178:179] op_sel_hi:[0,1,1] neg_lo:[1,0,0] neg_hi:[1,0,0]
	v_pk_fma_f32 v[138:139], v[138:139], v[172:173], v[176:177]
	v_pk_fma_f32 v[140:141], v[140:141], v[174:175], v[178:179]
	v_pk_mul_f32 v[144:145], v[138:139], v[186:187]
	v_pk_fma_f32 v[144:145], v[140:141], v[188:189], v[144:145]
	v_add_f32 v146, v144, v145
	ds_read_b128 v[230:233], v5 offset:47616
	ds_read_b128 v[234:237], v5 offset:47872
	ds_read_b128 v[238:241], v5 offset:48128
	ds_read_b128 v[242:245], v5 offset:48384
	ds_read_b128 v[246:249], v5 offset:48640
	ds_read_b32 v250, v9 offset:47616
	v_add_f32_dpp v146, v146, v146 quad_perm:[1,0,3,2] row_mask:0xf bank_mask:0xf bound_ctrl:1
	v_pk_mul_f32 v[180:181], v[138:139], v[180:181]
	v_pk_fma_f32 v[180:181], v[140:141], v[182:183], v[180:181]
	v_add_f32_dpp v146, v146, v146 quad_perm:[2,3,0,1] row_mask:0xf bank_mask:0xf bound_ctrl:1
	v_add_f32 v160, v180, v181
	v_pk_mul_f32 v[198:199], v[198:199], v[206:207] op_sel_hi:[1,0]
	v_add_f32_dpp v146, v146, v146 row_half_mirror row_mask:0xf bank_mask:0xf bound_ctrl:1
	v_pk_mul_f32 v[200:201], v[200:201], v[206:207] op_sel_hi:[1,0]
	s_waitcnt lgkmcnt(6)
	v_add_f32_dpp v146, v146, v146 row_mirror row_mask:0xf bank_mask:0xf bound_ctrl:1
	v_pk_fma_f32 v[198:199], v[146:147], v[190:191], v[198:199] op_sel_hi:[0,1,1] neg_lo:[1,0,0] neg_hi:[1,0,0]
	v_pk_fma_f32 v[200:201], v[146:147], v[192:193], v[200:201] op_sel_hi:[0,1,1] neg_lo:[1,0,0] neg_hi:[1,0,0]
	v_pk_fma_f32 v[138:139], v[138:139], v[194:195], v[198:199]
	v_pk_fma_f32 v[140:141], v[140:141], v[196:197], v[200:201]
	v_pk_mul_f32 v[144:145], v[138:139], v[208:209]
	v_pk_fma_f32 v[144:145], v[140:141], v[210:211], v[144:145]
	v_add_f32 v146, v144, v145
	s_nop 1
	v_add_f32_dpp v146, v146, v146 quad_perm:[1,0,3,2] row_mask:0xf bank_mask:0xf bound_ctrl:1
	v_pk_mul_f32 v[202:203], v[138:139], v[202:203]
	v_pk_fma_f32 v[202:203], v[140:141], v[204:205], v[202:203]
	v_add_f32_dpp v146, v146, v146 quad_perm:[2,3,0,1] row_mask:0xf bank_mask:0xf bound_ctrl:1
	v_add_f32 v161, v202, v203
	v_pk_mul_f32 v[220:221], v[220:221], v[228:229] op_sel_hi:[1,0]
	v_add_f32_dpp v146, v146, v146 row_half_mirror row_mask:0xf bank_mask:0xf bound_ctrl:1
	v_pk_mul_f32 v[222:223], v[222:223], v[228:229] op_sel_hi:[1,0]
	s_waitcnt lgkmcnt(0)
	v_add_f32_dpp v146, v146, v146 row_mirror row_mask:0xf bank_mask:0xf bound_ctrl:1
	v_pk_fma_f32 v[220:221], v[146:147], v[212:213], v[220:221] op_sel_hi:[0,1,1] neg_lo:[1,0,0] neg_hi:[1,0,0]
	v_pk_fma_f32 v[222:223], v[146:147], v[214:215], v[222:223] op_sel_hi:[0,1,1] neg_lo:[1,0,0] neg_hi:[1,0,0]
	v_pk_fma_f32 v[138:139], v[138:139], v[216:217], v[220:221]
	v_pk_fma_f32 v[140:141], v[140:141], v[218:219], v[222:223]
	v_pk_mul_f32 v[144:145], v[138:139], v[230:231]
	v_pk_fma_f32 v[144:145], v[140:141], v[232:233], v[144:145]
	v_add_f32 v146, v144, v145
	s_nop 1
	v_add_f32_dpp v146, v146, v146 quad_perm:[1,0,3,2] row_mask:0xf bank_mask:0xf bound_ctrl:1
	v_pk_mul_f32 v[224:225], v[138:139], v[224:225]
	v_pk_fma_f32 v[224:225], v[140:141], v[226:227], v[224:225]
	v_add_f32_dpp v146, v146, v146 quad_perm:[2,3,0,1] row_mask:0xf bank_mask:0xf bound_ctrl:1
	v_add_f32 v162, v224, v225
	v_pk_mul_f32 v[242:243], v[242:243], v[250:251] op_sel_hi:[1,0]
	v_add_f32_dpp v146, v146, v146 row_half_mirror row_mask:0xf bank_mask:0xf bound_ctrl:1
	v_pk_mul_f32 v[244:245], v[244:245], v[250:251] op_sel_hi:[1,0]
	s_nop 0
	v_add_f32_dpp v146, v146, v146 row_mirror row_mask:0xf bank_mask:0xf bound_ctrl:1
	v_pk_fma_f32 v[242:243], v[146:147], v[234:235], v[242:243] op_sel_hi:[0,1,1] neg_lo:[1,0,0] neg_hi:[1,0,0]
	v_pk_fma_f32 v[244:245], v[146:147], v[236:237], v[244:245] op_sel_hi:[0,1,1] neg_lo:[1,0,0] neg_hi:[1,0,0]
	v_pk_fma_f32 v[138:139], v[138:139], v[238:239], v[242:243]
	v_pk_fma_f32 v[140:141], v[140:141], v[240:241], v[244:245]
	v_pk_mul_f32 v[246:247], v[138:139], v[246:247]
	v_pk_fma_f32 v[246:247], v[140:141], v[248:249], v[246:247]
	v_add_f32 v163, v246, v247
	s_nop 0
	v_and_b32 v244, 8, v3
	v_cmp_ne_u32 vcc, 0, v244
	v_cndmask_b32 v244, v156, v148, vcc
	v_cndmask_b32 v245, v157, v149, vcc
	v_cndmask_b32 v246, v158, v150, vcc
	v_cndmask_b32 v247, v159, v151, vcc
	v_cndmask_b32 v230, v148, v156, vcc
	v_cndmask_b32 v231, v149, v157, vcc
	v_cndmask_b32 v232, v150, v158, vcc
	v_cndmask_b32 v233, v151, v159, vcc
	v_add_f32_dpp v230, v244, v230 row_mirror row_mask:0xf bank_mask:0xf bound_ctrl:1
	v_add_f32_dpp v231, v245, v231 row_mirror row_mask:0xf bank_mask:0xf bound_ctrl:1
	v_add_f32_dpp v232, v246, v232 row_mirror row_mask:0xf bank_mask:0xf bound_ctrl:1
	v_add_f32_dpp v233, v247, v233 row_mirror row_mask:0xf bank_mask:0xf bound_ctrl:1
	v_cndmask_b32 v244, v160, v152, vcc
	v_cndmask_b32 v245, v161, v153, vcc
	v_cndmask_b32 v246, v162, v154, vcc
	v_cndmask_b32 v247, v163, v155, vcc
	v_cndmask_b32 v234, v152, v160, vcc
	v_cndmask_b32 v235, v153, v161, vcc
	v_cndmask_b32 v236, v154, v162, vcc
	v_cndmask_b32 v237, v155, v163, vcc
	v_add_f32_dpp v234, v244, v234 row_mirror row_mask:0xf bank_mask:0xf bound_ctrl:1
	v_add_f32_dpp v235, v245, v235 row_mirror row_mask:0xf bank_mask:0xf bound_ctrl:1
	v_add_f32_dpp v236, v246, v236 row_mirror row_mask:0xf bank_mask:0xf bound_ctrl:1
	v_add_f32_dpp v237, v247, v237 row_mirror row_mask:0xf bank_mask:0xf bound_ctrl:1
	v_and_b32 v244, 4, v3
	v_cmp_ne_u32 vcc, 0, v244
	v_cndmask_b32 v244, v234, v230, vcc
	v_cndmask_b32 v245, v235, v231, vcc
	v_cndmask_b32 v246, v236, v232, vcc
	v_cndmask_b32 v247, v237, v233, vcc
	v_cndmask_b32 v238, v230, v234, vcc
	v_cndmask_b32 v239, v231, v235, vcc
	v_cndmask_b32 v240, v232, v236, vcc
	v_cndmask_b32 v241, v233, v237, vcc
	v_add_f32_dpp v238, v244, v238 row_half_mirror row_mask:0xf bank_mask:0xf bound_ctrl:1
	v_add_f32_dpp v239, v245, v239 row_half_mirror row_mask:0xf bank_mask:0xf bound_ctrl:1
	v_add_f32_dpp v240, v246, v240 row_half_mirror row_mask:0xf bank_mask:0xf bound_ctrl:1
	v_add_f32_dpp v241, v247, v241 row_half_mirror row_mask:0xf bank_mask:0xf bound_ctrl:1
	v_and_b32 v244, 2, v3
	v_cmp_ne_u32 vcc, 0, v244
	v_cndmask_b32 v244, v240, v238, vcc
	v_cndmask_b32 v245, v241, v239, vcc
	v_cndmask_b32 v242, v238, v240, vcc
	v_cndmask_b32 v243, v239, v241, vcc
	v_add_f32_dpp v242, v244, v242 quad_perm:[2,3,0,1] row_mask:0xf bank_mask:0xf bound_ctrl:1
	v_add_f32_dpp v243, v245, v243 quad_perm:[2,3,0,1] row_mask:0xf bank_mask:0xf bound_ctrl:1
	v_and_b32 v244, 1, v3
	v_cmp_ne_u32 vcc, 0, v244
	v_cndmask_b32 v244, v243, v242, vcc
	v_cndmask_b32 v245, v242, v243, vcc
	s_nop 0
	v_add_f32_dpp v19, v244, v245 quad_perm:[1,0,3,2] row_mask:0xf bank_mask:0xf bound_ctrl:1
	v_mov_b32 v2, v138
	v_mov_b32 v13, v139
	v_mov_b32 v12, v140
	v_mov_b32 v8, v141

; #define SCAN_BAR() asm volatile("s_barrier" ::: "memory")
; __device__ __forceinline__ void scan_unit(const Ctx& C0, const float* scn, int T, int quarter, const float* S0, float* Sout, unsigned char* obase, int mode) {
;     ...
;             if (mode == 0) { *(float*)(obase + (size_t)(k * 32 + q) * UPITCH_B + rl * 4) = osel0; *(float*)(obase + (size_t)(k * 32 + 16 + q) * UPITCH_B + rl * 4) = osel1; }
;             SCAN_BAR();
	v_lshl_add_u64 v[14:15], v[6:7], 0, s[0:1]
	v_add_co_u32_e32 v16, vcc, 0xfc29000, v14
	s_mov_b32 s8, 0xfc7f000
	s_nop 0
	v_addc_co_u32_e32 v17, vcc, 0, v15, vcc
	global_store_dword v[16:17], v18, off offset:768
	v_add_co_u32_e32 v16, vcc, 0xfc54000, v14
	s_add_u32 s0, s0, 0xac000
	s_nop 0
	v_addc_co_u32_e32 v17, vcc, 0, v15, vcc
	global_store_dword v[16:17], v19, off offset:768
	s_barrier
	v_mov_b32 v138, v2
	v_mov_b32 v139, v13
	v_mov_b32 v140, v12
	v_mov_b32 v141, v8
	ds_read_b128 v[164:167], v10 offset:0
	ds_read_b128 v[168:171], v10 offset:256
	ds_read_b128 v[172:175], v10 offset:512
	ds_read_b128 v[176:179], v10 offset:768
	ds_read_b128 v[180:183], v10 offset:1024
	ds_read_b32 v184, v11 offset:0
	ds_read_b128 v[186:189], v10 offset:1536
	ds_read_b128 v[190:193], v10 offset:1792
	ds_read_b128 v[194:197], v10 offset:2048
	ds_read_b128 v[198:201], v10 offset:2304
	ds_read_b128 v[202:205], v10 offset:2560
	ds_read_b32 v206, v11 offset:1536
	s_waitcnt lgkmcnt(0)
	v_pk_mul_f32 v[144:145], v[138:139], v[164:165]
	v_pk_fma_f32 v[144:145], v[140:141], v[166:167], v[144:145]
	v_add_f32 v146, v144, v145
	ds_read_b128 v[208:211], v10 offset:3072
	ds_read_b128 v[212:215], v10 offset:3328
	ds_read_b128 v[216:219], v10 offset:3584
	ds_read_b128 v[220:223], v10 offset:3840
	ds_read_b128 v[224:227], v10 offset:4096
	ds_read_b32 v228, v11 offset:3072
	v_add_f32_dpp v146, v146, v146 quad_perm:[1,0,3,2] row_mask:0xf bank_mask:0xf bound_ctrl:1
	s_nop 0
	s_nop 0
	v_add_f32_dpp v146, v146, v146 quad_perm:[2,3,0,1] row_mask:0xf bank_mask:0xf bound_ctrl:1
	s_nop 0
	v_pk_mul_f32 v[176:177], v[176:177], v[184:185] op_sel_hi:[1,0]
	v_add_f32_dpp v146, v146, v146 row_half_mirror row_mask:0xf bank_mask:0xf bound_ctrl:1
	v_pk_mul_f32 v[178:179], v[178:179], v[184:185] op_sel_hi:[1,0]
	s_waitcnt lgkmcnt(6)
	v_add_f32_dpp v146, v146, v146 row_mirror row_mask:0xf bank_mask:0xf bound_ctrl:1
	v_pk_fma_f32 v[176:177], v[146:147], v[168:169], v[176:177] op_sel_hi:[0,1,1] neg_lo:[1,0,0] neg_hi:[1,0,0]
	v_pk_fma_f32 v[178:179], v[146:147], v[170:171], v[178:179] op_sel_hi:[0,1,1] neg_lo:[1,0,0] neg_hi:[1,0,0]
	v_pk_fma_f32 v[138:139], v[138:139], v[172:173], v[176:177]
	v_pk_fma_f32 v[140:141], v[140:141], v[174:175], v[178:179]
	v_pk_mul_f32 v[144:145], v[138:139], v[186:187]
	v_pk_fma_f32 v[144:145], v[140:141], v[188:189], v[144:145]
	v_add_f32 v146, v144, v145
	ds_read_b128 v[230:233], v10 offset:4608
	ds_read_b128 v[234:237], v10 offset:4864
	ds_read_b128 v[238:241], v10 offset:5120
	ds_read_b128 v[242:245], v10 offset:5376
	ds_read_b128 v[246:249], v10 offset:5632
	ds_read_b32 v250, v11 offset:4608
	v_add_f32_dpp v146, v146, v146 quad_perm:[1,0,3,2] row_mask:0xf bank_mask:0xf bound_ctrl:1
	v_pk_mul_f32 v[180:181], v[138:139], v[180:181]
	v_pk_fma_f32 v[180:181], v[140:141], v[182:183], v[180:181]
	v_add_f32_dpp v146, v146, v146 quad_perm:[2,3,0,1] row_mask:0xf bank_mask:0xf bound_ctrl:1
	v_add_f32 v148, v180, v181
	v_pk_mul_f32 v[198:199], v[198:199], v[206:207] op_sel_hi:[1,0]
	v_add_f32_dpp v146, v146, v146 row_half_mirror row_mask:0xf bank_mask:0xf bound_ctrl:1
	v_pk_mul_f32 v[200:201], v[200:201], v[206:207] op_sel_hi:[1,0]
	s_waitcnt lgkmcnt(6)
	v_add_f32_dpp v146, v146, v146 row_mirror row_mask:0xf bank_mask:0xf bound_ctrl:1
	v_pk_fma_f32 v[198:199], v[146:147], v[190:191], v[198:199] op_sel_hi:[0,1,1] neg_lo:[1,0,0] neg_hi:[1,0,0]
	v_pk_fma_f32 v[200:201], v[146:147], v[192:193], v[200:201] op_sel_hi:[0,1,1] neg_lo:[1,0,0] neg_hi:[1,0,0]
	v_pk_fma_f32 v[138:139], v[138:139], v[194:195], v[198:199]
	v_pk_fma_f32 v[140:141], v[140:141], v[196:197], v[200:201]
	v_pk_mul_f32 v[144:145], v[138:139], v[208:209]
	v_pk_fma_f32 v[144:145], v[140:141], v[210:211], v[144:145]
	v_add_f32 v146, v144, v145
	ds_read_b128 v[164:167], v10 offset:6144
	ds_read_b128 v[168:171], v10 offset:6400
	ds_read_b128 v[172:175], v10 offset:6656
	ds_read_b128 v[176:179], v10 offset:6912
	ds_read_b128 v[180:183], v10 offset:7168
	ds_read_b32 v184, v11 offset:6144
	v_add_f32_dpp v146, v146, v146 quad_perm:[1,0,3,2] row_mask:0xf bank_mask:0xf bound_ctrl:1
	v_pk_mul_f32 v[202:203], v[138:139], v[202:203]
	v_pk_fma_f32 v[202:203], v[140:141], v[204:205], v[202:203]
	v_add_f32_dpp v146, v146, v146 quad_perm:[2,3,0,1] row_mask:0xf bank_mask:0xf bound_ctrl:1
	v_add_f32 v149, v202, v203
	v_pk_mul_f32 v[220:221], v[220:221], v[228:229] op_sel_hi:[1,0]
	v_add_f32_dpp v146, v146, v146 row_half_mirror row_mask:0xf bank_mask:0xf bound_ctrl:1
	v_pk_mul_f32 v[222:223], v[222:223], v[228:229] op_sel_hi:[1,0]
	s_waitcnt lgkmcnt(6)
	v_add_f32_dpp v146, v146, v146 row_mirror row_mask:0xf bank_mask:0xf bound_ctrl:1
	v_pk_fma_f32 v[220:221], v[146:147], v[212:213], v[220:221] op_sel_hi:[0,1,1] neg_lo:[1,0,0] neg_hi:[1,0,0]
	v_pk_fma_f32 v[222:223], v[146:147], v[214:215], v[222:223] op_sel_hi:[0,1,1] neg_lo:[1,0,0] neg_hi:[1,0,0]
	v_pk_fma_f32 v[138:139], v[138:139], v[216:217], v[220:221]
	v_pk_fma_f32 v[140:141], v[140:141], v[218:219], v[222:223]
	v_pk_mul_f32 v[144:145], v[138:139], v[230:231]
	v_pk_fma_f32 v[144:145], v[140:141], v[232:233], v[144:145]
	v_add_f32 v146, v144, v145
	ds_read_b128 v[186:189], v10 offset:7680
	ds_read_b128 v[190:193], v10 offset:7936
	ds_read_b128 v[194:197], v10 offset:8192
	ds_read_b128 v[198:201], v10 offset:8448
	ds_read_b128 v[202:205], v10 offset:8704
	ds_read_b32 v206, v11 offset:7680
	v_add_f32_dpp v146, v146, v146 quad_perm:[1,0,3,2] row_mask:0xf bank_mask:0xf bound_ctrl:1
	v_pk_mul_f32 v[224:225], v[138:139], v[224:225]
	v_pk_fma_f32 v[224:225], v[140:141], v[226:227], v[224:225]
	v_add_f32_dpp v146, v146, v146 quad_perm:[2,3,0,1] row_mask:0xf bank_mask:0xf bound_ctrl:1
	v_add_f32 v150, v224, v225
	v_pk_mul_f32 v[242:243], v[242:243], v[250:251] op_sel_hi:[1,0]
	v_add_f32_dpp v146, v146, v146 row_half_mirror row_mask:0xf bank_mask:0xf bound_ctrl:1
	v_pk_mul_f32 v[244:245], v[244:245], v[250:251] op_sel_hi:[1,0]
	s_waitcnt lgkmcnt(6)
	v_add_f32_dpp v146, v146, v146 row_mirror row_mask:0xf bank_mask:0xf bound_ctrl:1
	v_pk_fma_f32 v[242:243], v[146:147], v[234:235], v[242:243] op_sel_hi:[0,1,1] neg_lo:[1,0,0] neg_hi:[1,0,0]
	v_pk_fma_f32 v[244:245], v[146:147], v[236:237], v[244:245] op_sel_hi:[0,1,1] neg_lo:[1,0,0] neg_hi:[1,0,0]
	v_pk_fma_f32 v[138:139], v[138:139], v[238:239], v[242:243]
	v_pk_fma_f32 v[140:141], v[140:141], v[240:241], v[244:245]
	v_pk_mul_f32 v[144:145], v[138:139], v[164:165]
	v_pk_fma_f32 v[144:145], v[140:141], v[166:167], v[144:145]
	v_add_f32 v146, v144, v145
	ds_read_b128 v[208:211], v10 offset:9216
	ds_read_b128 v[212:215], v10 offset:9472
	ds_read_b128 v[216:219], v10 offset:9728
	ds_read_b128 v[220:223], v10 offset:9984
	ds_read_b128 v[224:227], v10 offset:10240
	ds_read_b32 v228, v11 offset:9216
	v_add_f32_dpp v146, v146, v146 quad_perm:[1,0,3,2] row_mask:0xf bank_mask:0xf bound_ctrl:1
	v_pk_mul_f32 v[246:247], v[138:139], v[246:247]
	v_pk_fma_f32 v[246:247], v[140:141], v[248:249], v[246:247]
	v_add_f32_dpp v146, v146, v146 quad_perm:[2,3,0,1] row_mask:0xf bank_mask:0xf bound_ctrl:1
	v_add_f32 v151, v246, v247
	v_pk_mul_f32 v[176:177], v[176:177], v[184:185] op_sel_hi:[1,0]
	v_add_f32_dpp v146, v146, v146 row_half_mirror row_mask:0xf bank_mask:0xf bound_ctrl:1
	v_pk_mul_f32 v[178:179], v[178:179], v[184:185] op_sel_hi:[1,0]
	s_waitcnt lgkmcnt(6)
	v_add_f32_dpp v146, v146, v146 row_mirror row_mask:0xf bank_mask:0xf bound_ctrl:1
	v_pk_fma_f32 v[176:177], v[146:147], v[168:169], v[176:177] op_sel_hi:[0,1,1] neg_lo:[1,0,0] neg_hi:[1,0,0]
	v_pk_fma_f32 v[178:179], v[146:147], v[170:171], v[178:179] op_sel_hi:[0,1,1] neg_lo:[1,0,0] neg_hi:[1,0,0]
	v_pk_fma_f32 v[138:139], v[138:139], v[172:173], v[176:177]
	v_pk_fma_f32 v[140:141], v[140:141], v[174:175], v[178:179]
	v_pk_mul_f32 v[144:145], v[138:139], v[186:187]
	v_pk_fma_f32 v[144:145], v[140:141], v[188:189], v[144:145]
	v_add_f32 v146, v144, v145
	ds_read_b128 v[230:233], v10 offset:10752
	ds_read_b128 v[234:237], v10 offset:11008
	ds_read_b128 v[238:241], v10 offset:11264
	ds_read_b128 v[242:245], v10 offset:11520
	ds_read_b128 v[246:249], v10 offset:11776
	ds_read_b32 v250, v11 offset:10752
	v_add_f32_dpp v146, v146, v146 quad_perm:[1,0,3,2] row_mask:0xf bank_mask:0xf bound_ctrl:1
	v_pk_mul_f32 v[180:181], v[138:139], v[180:181]
	v_pk_fma_f32 v[180:181], v[140:141], v[182:183], v[180:181]
	v_add_f32_dpp v146, v146, v146 quad_perm:[2,3,0,1] row_mask:0xf bank_mask:0xf bound_ctrl:1
	v_add_f32 v152, v180, v181
	v_pk_mul_f32 v[198:199], v[198:199], v[206:207] op_sel_hi:[1,0]
	v_add_f32_dpp v146, v146, v146 row_half_mirror row_mask:0xf bank_mask:0xf bound_ctrl:1
	v_pk_mul_f32 v[200:201], v[200:201], v[206:207] op_sel_hi:[1,0]
	s_waitcnt lgkmcnt(6)
	v_add_f32_dpp v146, v146, v146 row_mirror row_mask:0xf bank_mask:0xf bound_ctrl:1
	v_pk_fma_f32 v[198:199], v[146:147], v[190:191], v[198:199] op_sel_hi:[0,1,1] neg_lo:[1,0,0] neg_hi:[1,0,0]
	v_pk_fma_f32 v[200:201], v[146:147], v[192:193], v[200:201] op_sel_hi:[0,1,1] neg_lo:[1,0,0] neg_hi:[1,0,0]
	v_pk_fma_f32 v[138:139], v[138:139], v[194:195], v[198:199]
	v_pk_fma_f32 v[140:141], v[140:141], v[196:197], v[200:201]
	v_pk_mul_f32 v[144:145], v[138:139], v[208:209]
	v_pk_fma_f32 v[144:145], v[140:141], v[210:211], v[144:145]
	v_add_f32 v146, v144, v145
	ds_read_b128 v[164:167], v10 offset:12288
	ds_read_b128 v[168:171], v10 offset:12544
	ds_read_b128 v[172:175], v10 offset:12800
	ds_read_b128 v[176:179], v10 offset:13056
	ds_read_b128 v[180:183], v10 offset:13312
	ds_read_b32 v184, v11 offset:12288
	v_add_f32_dpp v146, v146, v146 quad_perm:[1,0,3,2] row_mask:0xf bank_mask:0xf bound_ctrl:1
	v_pk_mul_f32 v[202:203], v[138:139], v[202:203]
	v_pk_fma_f32 v[202:203], v[140:141], v[204:205], v[202:203]
	v_add_f32_dpp v146, v146, v146 quad_perm:[2,3,0,1] row_mask:0xf bank_mask:0xf bound_ctrl:1
	v_add_f32 v153, v202, v203
	v_pk_mul_f32 v[220:221], v[220:221], v[228:229] op_sel_hi:[1,0]
	v_add_f32_dpp v146, v146, v146 row_half_mirror row_mask:0xf bank_mask:0xf bound_ctrl:1
	v_pk_mul_f32 v[222:223], v[222:223], v[228:229] op_sel_hi:[1,0]
	s_waitcnt lgkmcnt(6)
	v_add_f32_dpp v146, v146, v146 row_mirror row_mask:0xf bank_mask:0xf bound_ctrl:1
	v_pk_fma_f32 v[220:221], v[146:147], v[212:213], v[220:221] op_sel_hi:[0,1,1] neg_lo:[1,0,0] neg_hi:[1,0,0]
	v_pk_fma_f32 v[222:223], v[146:147], v[214:215], v[222:223] op_sel_hi:[0,1,1] neg_lo:[1,0,0] neg_hi:[1,0,0]
	v_pk_fma_f32 v[138:139], v[138:139], v[216:217], v[220:221]
	v_pk_fma_f32 v[140:141], v[140:141], v[218:219], v[222:223]
	v_pk_mul_f32 v[144:145], v[138:139], v[230:231]
	v_pk_fma_f32 v[144:145], v[140:141], v[232:233], v[144:145]
	v_add_f32 v146, v144, v145
	ds_read_b128 v[186:189], v10 offset:13824
	ds_read_b128 v[190:193], v10 offset:14080
	ds_read_b128 v[194:197], v10 offset:14336
	ds_read_b128 v[198:201], v10 offset:14592
	ds_read_b128 v[202:205], v10 offset:14848
	ds_read_b32 v206, v11 offset:13824
	v_add_f32_dpp v146, v146, v146 quad_perm:[1,0,3,2] row_mask:0xf bank_mask:0xf bound_ctrl:1
	v_pk_mul_f32 v[224:225], v[138:139], v[224:225]
	v_pk_fma_f32 v[224:225], v[140:141], v[226:227], v[224:225]
	v_add_f32_dpp v146, v146, v146 quad_perm:[2,3,0,1] row_mask:0xf bank_mask:0xf bound_ctrl:1
	v_add_f32 v154, v224, v225
	v_pk_mul_f32 v[242:243], v[242:243], v[250:251] op_sel_hi:[1,0]
	v_add_f32_dpp v146, v146, v146 row_half_mirror row_mask:0xf bank_mask:0xf bound_ctrl:1
	v_pk_mul_f32 v[244:245], v[244:245], v[250:251] op_sel_hi:[1,0]
	s_waitcnt lgkmcnt(6)
	v_add_f32_dpp v146, v146, v146 row_mirror row_mask:0xf bank_mask:0xf bound_ctrl:1
	v_pk_fma_f32 v[242:243], v[146:147], v[234:235], v[242:243] op_sel_hi:[0,1,1] neg_lo:[1,0,0] neg_hi:[1,0,0]
	v_pk_fma_f32 v[244:245], v[146:147], v[236:237], v[244:245] op_sel_hi:[0,1,1] neg_lo:[1,0,0] neg_hi:[1,0,0]
	v_pk_fma_f32 v[138:139], v[138:139], v[238:239], v[242:243]
	v_pk_fma_f32 v[140:141], v[140:141], v[240:241], v[244:245]
	v_pk_mul_f32 v[144:145], v[138:139], v[164:165]
	v_pk_fma_f32 v[144:145], v[140:141], v[166:167], v[144:145]
	v_add_f32 v146, v144, v145
	ds_read_b128 v[208:211], v10 offset:15360
	ds_read_b128 v[212:215], v10 offset:15616
	ds_read_b128 v[216:219], v10 offset:15872
	ds_read_b128 v[220:223], v10 offset:16128
	ds_read_b128 v[224:227], v10 offset:16384
	ds_read_b32 v228, v11 offset:15360
	v_add_f32_dpp v146, v146, v146 quad_perm:[1,0,3,2] row_mask:0xf bank_mask:0xf bound_ctrl:1
	v_pk_mul_f32 v[246:247], v[138:139], v[246:247]
	v_pk_fma_f32 v[246:247], v[140:141], v[248:249], v[246:247]
	v_add_f32_dpp v146, v146, v146 quad_perm:[2,3,0,1] row_mask:0xf bank_mask:0xf bound_ctrl:1
	v_add_f32 v155, v246, v247
	v_pk_mul_f32 v[176:177], v[176:177], v[184:185] op_sel_hi:[1,0]
	v_add_f32_dpp v146, v146, v146 row_half_mirror row_mask:0xf bank_mask:0xf bound_ctrl:1
	v_pk_mul_f32 v[178:179], v[178:179], v[184:185] op_sel_hi:[1,0]
	s_waitcnt lgkmcnt(6)
	v_add_f32_dpp v146, v146, v146 row_mirror row_mask:0xf bank_mask:0xf bound_ctrl:1
	v_pk_fma_f32 v[176:177], v[146:147], v[168:169], v[176:177] op_sel_hi:[0,1,1] neg_lo:[1,0,0] neg_hi:[1,0,0]
	v_pk_fma_f32 v[178:179], v[146:147], v[170:171], v[178:179] op_sel_hi:[0,1,1] neg_lo:[1,0,0] neg_hi:[1,0,0]
	v_pk_fma_f32 v[138:139], v[138:139], v[172:173], v[176:177]
	v_pk_fma_f32 v[140:141], v[140:141], v[174:175], v[178:179]
	v_pk_mul_f32 v[144:145], v[138:139], v[186:187]
	v_pk_fma_f32 v[144:145], v[140:141], v[188:189], v[144:145]
	v_add_f32 v146, v144, v145
	ds_read_b128 v[230:233], v10 offset:16896
	ds_read_b128 v[234:237], v10 offset:17152
	ds_read_b128 v[238:241], v10 offset:17408
	ds_read_b128 v[242:245], v10 offset:17664
	ds_read_b128 v[246:249], v10 offset:17920
	ds_read_b32 v250, v11 offset:16896
	v_add_f32_dpp v146, v146, v146 quad_perm:[1,0,3,2] row_mask:0xf bank_mask:0xf bound_ctrl:1
	v_pk_mul_f32 v[180:181], v[138:139], v[180:181]
	v_pk_fma_f32 v[180:181], v[140:141], v[182:183], v[180:181]
	v_add_f32_dpp v146, v146, v146 quad_perm:[2,3,0,1] row_mask:0xf bank_mask:0xf bound_ctrl:1
	v_add_f32 v156, v180, v181
	v_pk_mul_f32 v[198:199], v[198:199], v[206:207] op_sel_hi:[1,0]
	v_add_f32_dpp v146, v146, v146 row_half_mirror row_mask:0xf bank_mask:0xf bound_ctrl:1
	v_pk_mul_f32 v[200:201], v[200:201], v[206:207] op_sel_hi:[1,0]
	s_waitcnt lgkmcnt(6)
	v_add_f32_dpp v146, v146, v146 row_mirror row_mask:0xf bank_mask:0xf bound_ctrl:1
	v_pk_fma_f32 v[198:199], v[146:147], v[190:191], v[198:199] op_sel_hi:[0,1,1] neg_lo:[1,0,0] neg_hi:[1,0,0]
	v_pk_fma_f32 v[200:201], v[146:147], v[192:193], v[200:201] op_sel_hi:[0,1,1] neg_lo:[1,0,0] neg_hi:[1,0,0]
	v_pk_fma_f32 v[138:139], v[138:139], v[194:195], v[198:199]
	v_pk_fma_f32 v[140:141], v[140:141], v[196:197], v[200:201]
	v_pk_mul_f32 v[144:145], v[138:139], v[208:209]
	v_pk_fma_f32 v[144:145], v[140:141], v[210:211], v[144:145]
	v_add_f32 v146, v144, v145
	ds_read_b128 v[164:167], v10 offset:18432
	ds_read_b128 v[168:171], v10 offset:18688
	ds_read_b128 v[172:175], v10 offset:18944
	ds_read_b128 v[176:179], v10 offset:19200
	ds_read_b128 v[180:183], v10 offset:19456
	ds_read_b32 v184, v11 offset:18432
	v_add_f32_dpp v146, v146, v146 quad_perm:[1,0,3,2] row_mask:0xf bank_mask:0xf bound_ctrl:1
	v_pk_mul_f32 v[202:203], v[138:139], v[202:203]
	v_pk_fma_f32 v[202:203], v[140:141], v[204:205], v[202:203]
	v_add_f32_dpp v146, v146, v146 quad_perm:[2,3,0,1] row_mask:0xf bank_mask:0xf bound_ctrl:1
	v_add_f32 v157, v202, v203
	v_pk_mul_f32 v[220:221], v[220:221], v[228:229] op_sel_hi:[1,0]
	v_add_f32_dpp v146, v146, v146 row_half_mirror row_mask:0xf bank_mask:0xf bound_ctrl:1
	v_pk_mul_f32 v[222:223], v[222:223], v[228:229] op_sel_hi:[1,0]
	s_waitcnt lgkmcnt(6)
	v_add_f32_dpp v146, v146, v146 row_mirror row_mask:0xf bank_mask:0xf bound_ctrl:1
	v_pk_fma_f32 v[220:221], v[146:147], v[212:213], v[220:221] op_sel_hi:[0,1,1] neg_lo:[1,0,0] neg_hi:[1,0,0]
	v_pk_fma_f32 v[222:223], v[146:147], v[214:215], v[222:223] op_sel_hi:[0,1,1] neg_lo:[1,0,0] neg_hi:[1,0,0]
	v_pk_fma_f32 v[138:139], v[138:139], v[216:217], v[220:221]
	v_pk_fma_f32 v[140:141], v[140:141], v[218:219], v[222:223]
	v_pk_mul_f32 v[144:145], v[138:139], v[230:231]
	v_pk_fma_f32 v[144:145], v[140:141], v[232:233], v[144:145]
	v_add_f32 v146, v144, v145
	ds_read_b128 v[186:189], v10 offset:19968
	ds_read_b128 v[190:193], v10 offset:20224
	ds_read_b128 v[194:197], v10 offset:20480
	ds_read_b128 v[198:201], v10 offset:20736
	ds_read_b128 v[202:205], v10 offset:20992
	ds_read_b32 v206, v11 offset:19968
	v_add_f32_dpp v146, v146, v146 quad_perm:[1,0,3,2] row_mask:0xf bank_mask:0xf bound_ctrl:1
	v_pk_mul_f32 v[224:225], v[138:139], v[224:225]
	v_pk_fma_f32 v[224:225], v[140:141], v[226:227], v[224:225]
	v_add_f32_dpp v146, v146, v146 quad_perm:[2,3,0,1] row_mask:0xf bank_mask:0xf bound_ctrl:1
	v_add_f32 v158, v224, v225
	v_pk_mul_f32 v[242:243], v[242:243], v[250:251] op_sel_hi:[1,0]
	v_add_f32_dpp v146, v146, v146 row_half_mirror row_mask:0xf bank_mask:0xf bound_ctrl:1
	v_pk_mul_f32 v[244:245], v[244:245], v[250:251] op_sel_hi:[1,0]
	s_waitcnt lgkmcnt(6)
	v_add_f32_dpp v146, v146, v146 row_mirror row_mask:0xf bank_mask:0xf bound_ctrl:1
	v_pk_fma_f32 v[242:243], v[146:147], v[234:235], v[242:243] op_sel_hi:[0,1,1] neg_lo:[1,0,0] neg_hi:[1,0,0]
	v_pk_fma_f32 v[244:245], v[146:147], v[236:237], v[244:245] op_sel_hi:[0,1,1] neg_lo:[1,0,0] neg_hi:[1,0,0]
	v_pk_fma_f32 v[138:139], v[138:139], v[238:239], v[242:243]
	v_pk_fma_f32 v[140:141], v[140:141], v[240:241], v[244:245]
	v_pk_mul_f32 v[144:145], v[138:139], v[164:165]
	v_pk_fma_f32 v[144:145], v[140:141], v[166:167], v[144:145]
	v_add_f32 v146, v144, v145
	ds_read_b128 v[208:211], v10 offset:21504
	ds_read_b128 v[212:215], v10 offset:21760
	ds_read_b128 v[216:219], v10 offset:22016
	ds_read_b128 v[220:223], v10 offset:22272
	ds_read_b128 v[224:227], v10 offset:22528
	ds_read_b32 v228, v11 offset:21504
	v_add_f32_dpp v146, v146, v146 quad_perm:[1,0,3,2] row_mask:0xf bank_mask:0xf bound_ctrl:1
	v_pk_mul_f32 v[246:247], v[138:139], v[246:247]
	v_pk_fma_f32 v[246:247], v[140:141], v[248:249], v[246:247]
	v_add_f32_dpp v146, v146, v146 quad_perm:[2,3,0,1] row_mask:0xf bank_mask:0xf bound_ctrl:1
	v_add_f32 v159, v246, v247
	v_pk_mul_f32 v[176:177], v[176:177], v[184:185] op_sel_hi:[1,0]
	v_add_f32_dpp v146, v146, v146 row_half_mirror row_mask:0xf bank_mask:0xf bound_ctrl:1
	v_pk_mul_f32 v[178:179], v[178:179], v[184:185] op_sel_hi:[1,0]
	s_waitcnt lgkmcnt(6)
	v_add_f32_dpp v146, v146, v146 row_mirror row_mask:0xf bank_mask:0xf bound_ctrl:1
	v_pk_fma_f32 v[176:177], v[146:147], v[168:169], v[176:177] op_sel_hi:[0,1,1] neg_lo:[1,0,0] neg_hi:[1,0,0]
	v_pk_fma_f32 v[178:179], v[146:147], v[170:171], v[178:179] op_sel_hi:[0,1,1] neg_lo:[1,0,0] neg_hi:[1,0,0]
	v_pk_fma_f32 v[138:139], v[138:139], v[172:173], v[176:177]
	v_pk_fma_f32 v[140:141], v[140:141], v[174:175], v[178:179]
	v_pk_mul_f32 v[144:145], v[138:139], v[186:187]
	v_pk_fma_f32 v[144:145], v[140:141], v[188:189], v[144:145]
	v_add_f32 v146, v144, v145
	ds_read_b128 v[230:233], v10 offset:23040
	ds_read_b128 v[234:237], v10 offset:23296
	ds_read_b128 v[238:241], v10 offset:23552
	ds_read_b128 v[242:245], v10 offset:23808
	ds_read_b128 v[246:249], v10 offset:24064
	ds_read_b32 v250, v11 offset:23040
	v_add_f32_dpp v146, v146, v146 quad_perm:[1,0,3,2] row_mask:0xf bank_mask:0xf bound_ctrl:1
	v_pk_mul_f32 v[180:181], v[138:139], v[180:181]
	v_pk_fma_f32 v[180:181], v[140:141], v[182:183], v[180:181]
	v_add_f32_dpp v146, v146, v146 quad_perm:[2,3,0,1] row_mask:0xf bank_mask:0xf bound_ctrl:1
	v_add_f32 v160, v180, v181
	v_pk_mul_f32 v[198:199], v[198:199], v[206:207] op_sel_hi:[1,0]
	v_add_f32_dpp v146, v146, v146 row_half_mirror row_mask:0xf bank_mask:0xf bound_ctrl:1
	v_pk_mul_f32 v[200:201], v[200:201], v[206:207] op_sel_hi:[1,0]
	s_waitcnt lgkmcnt(6)
	v_add_f32_dpp v146, v146, v146 row_mirror row_mask:0xf bank_mask:0xf bound_ctrl:1
	v_pk_fma_f32 v[198:199], v[146:147], v[190:191], v[198:199] op_sel_hi:[0,1,1] neg_lo:[1,0,0] neg_hi:[1,0,0]
	v_pk_fma_f32 v[200:201], v[146:147], v[192:193], v[200:201] op_sel_hi:[0,1,1] neg_lo:[1,0,0] neg_hi:[1,0,0]
	v_pk_fma_f32 v[138:139], v[138:139], v[194:195], v[198:199]
	v_pk_fma_f32 v[140:141], v[140:141], v[196:197], v[200:201]
	v_pk_mul_f32 v[144:145], v[138:139], v[208:209]
	v_pk_fma_f32 v[144:145], v[140:141], v[210:211], v[144:145]
	v_add_f32 v146, v144, v145
	ds_read_b128 v[164:167], v10 offset:24576
	ds_read_b128 v[168:171], v10 offset:24832
	ds_read_b128 v[172:175], v10 offset:25088
	ds_read_b128 v[176:179], v10 offset:25344
	ds_read_b128 v[180:183], v10 offset:25600
	ds_read_b32 v184, v11 offset:24576
	v_add_f32_dpp v146, v146, v146 quad_perm:[1,0,3,2] row_mask:0xf bank_mask:0xf bound_ctrl:1
	v_pk_mul_f32 v[202:203], v[138:139], v[202:203]
	v_pk_fma_f32 v[202:203], v[140:141], v[204:205], v[202:203]
	v_add_f32_dpp v146, v146, v146 quad_perm:[2,3,0,1] row_mask:0xf bank_mask:0xf bound_ctrl:1
	v_add_f32 v161, v202, v203
	v_pk_mul_f32 v[220:221], v[220:221], v[228:229] op_sel_hi:[1,0]
	v_add_f32_dpp v146, v146, v146 row_half_mirror row_mask:0xf bank_mask:0xf bound_ctrl:1
	v_pk_mul_f32 v[222:223], v[222:223], v[228:229] op_sel_hi:[1,0]
	s_waitcnt lgkmcnt(6)
	v_add_f32_dpp v146, v146, v146 row_mirror row_mask:0xf bank_mask:0xf bound_ctrl:1
	v_pk_fma_f32 v[220:221], v[146:147], v[212:213], v[220:221] op_sel_hi:[0,1,1] neg_lo:[1,0,0] neg_hi:[1,0,0]
	v_pk_fma_f32 v[222:223], v[146:147], v[214:215], v[222:223] op_sel_hi:[0,1,1] neg_lo:[1,0,0] neg_hi:[1,0,0]
	v_pk_fma_f32 v[138:139], v[138:139], v[216:217], v[220:221]
	v_pk_fma_f32 v[140:141], v[140:141], v[218:219], v[222:223]
	v_pk_mul_f32 v[144:145], v[138:139], v[230:231]
	v_pk_fma_f32 v[144:145], v[140:141], v[232:233], v[144:145]
	v_add_f32 v146, v144, v145
	ds_read_b128 v[186:189], v10 offset:26112
	ds_read_b128 v[190:193], v10 offset:26368
	ds_read_b128 v[194:197], v10 offset:26624
	ds_read_b128 v[198:201], v10 offset:26880
	ds_read_b128 v[202:205], v10 offset:27136
	ds_read_b32 v206, v11 offset:26112
	v_add_f32_dpp v146, v146, v146 quad_perm:[1,0,3,2] row_mask:0xf bank_mask:0xf bound_ctrl:1
	v_pk_mul_f32 v[224:225], v[138:139], v[224:225]
	v_pk_fma_f32 v[224:225], v[140:141], v[226:227], v[224:225]
	v_add_f32_dpp v146, v146, v146 quad_perm:[2,3,0,1] row_mask:0xf bank_mask:0xf bound_ctrl:1
	v_add_f32 v162, v224, v225
	v_pk_mul_f32 v[242:243], v[242:243], v[250:251] op_sel_hi:[1,0]
	v_add_f32_dpp v146, v146, v146 row_half_mirror row_mask:0xf bank_mask:0xf bound_ctrl:1
	v_pk_mul_f32 v[244:245], v[244:245], v[250:251] op_sel_hi:[1,0]
	s_waitcnt lgkmcnt(6)
	v_add_f32_dpp v146, v146, v146 row_mirror row_mask:0xf bank_mask:0xf bound_ctrl:1
	v_pk_fma_f32 v[242:243], v[146:147], v[234:235], v[242:243] op_sel_hi:[0,1,1] neg_lo:[1,0,0] neg_hi:[1,0,0]
	v_pk_fma_f32 v[244:245], v[146:147], v[236:237], v[244:245] op_sel_hi:[0,1,1] neg_lo:[1,0,0] neg_hi:[1,0,0]
	v_pk_fma_f32 v[138:139], v[138:139], v[238:239], v[242:243]
	v_pk_fma_f32 v[140:141], v[140:141], v[240:241], v[244:245]
	v_pk_mul_f32 v[144:145], v[138:139], v[164:165]
	v_pk_fma_f32 v[144:145], v[140:141], v[166:167], v[144:145]
	v_add_f32 v146, v144, v145
	ds_read_b128 v[208:211], v10 offset:27648
	ds_read_b128 v[212:215], v10 offset:27904
	ds_read_b128 v[216:219], v10 offset:28160
	ds_read_b128 v[220:223], v10 offset:28416
	ds_read_b128 v[224:227], v10 offset:28672
	ds_read_b32 v228, v11 offset:27648
	v_add_f32_dpp v146, v146, v146 quad_perm:[1,0,3,2] row_mask:0xf bank_mask:0xf bound_ctrl:1
	v_pk_mul_f32 v[246:247], v[138:139], v[246:247]
	v_pk_fma_f32 v[246:247], v[140:141], v[248:249], v[246:247]
	v_add_f32_dpp v146, v146, v146 quad_perm:[2,3,0,1] row_mask:0xf bank_mask:0xf bound_ctrl:1
	v_add_f32 v163, v246, v247
	v_pk_mul_f32 v[176:177], v[176:177], v[184:185] op_sel_hi:[1,0]
	v_add_f32_dpp v146, v146, v146 row_half_mirror row_mask:0xf bank_mask:0xf bound_ctrl:1
	v_pk_mul_f32 v[178:179], v[178:179], v[184:185] op_sel_hi:[1,0]
	s_waitcnt lgkmcnt(6)
	v_add_f32_dpp v146, v146, v146 row_mirror row_mask:0xf bank_mask:0xf bound_ctrl:1
	v_pk_fma_f32 v[176:177], v[146:147], v[168:169], v[176:177] op_sel_hi:[0,1,1] neg_lo:[1,0,0] neg_hi:[1,0,0]
	v_pk_fma_f32 v[178:179], v[146:147], v[170:171], v[178:179] op_sel_hi:[0,1,1] neg_lo:[1,0,0] neg_hi:[1,0,0]
	v_pk_fma_f32 v[138:139], v[138:139], v[172:173], v[176:177]
	v_pk_fma_f32 v[140:141], v[140:141], v[174:175], v[178:179]
	v_pk_mul_f32 v[144:145], v[138:139], v[186:187]
	v_pk_fma_f32 v[144:145], v[140:141], v[188:189], v[144:145]
	v_add_f32 v146, v144, v145
	v_and_b32 v244, 8, v3
	v_cmp_ne_u32 vcc, 0, v244
	v_cndmask_b32 v244, v156, v148, vcc
	v_cndmask_b32 v245, v157, v149, vcc
	v_cndmask_b32 v246, v158, v150, vcc
	v_cndmask_b32 v247, v159, v151, vcc
	v_cndmask_b32 v230, v148, v156, vcc
	v_cndmask_b32 v231, v149, v157, vcc
	v_cndmask_b32 v232, v150, v158, vcc
	v_cndmask_b32 v233, v151, v159, vcc
	v_add_f32_dpp v230, v244, v230 row_mirror row_mask:0xf bank_mask:0xf bound_ctrl:1
	v_add_f32_dpp v231, v245, v231 row_mirror row_mask:0xf bank_mask:0xf bound_ctrl:1
	v_add_f32_dpp v232, v246, v232 row_mirror row_mask:0xf bank_mask:0xf bound_ctrl:1
	v_add_f32_dpp v233, v247, v233 row_mirror row_mask:0xf bank_mask:0xf bound_ctrl:1
	v_cndmask_b32 v244, v160, v152, vcc
	v_cndmask_b32 v245, v161, v153, vcc
	v_cndmask_b32 v246, v162, v154, vcc
	v_cndmask_b32 v247, v163, v155, vcc
	v_cndmask_b32 v234, v152, v160, vcc
	v_cndmask_b32 v235, v153, v161, vcc
	v_cndmask_b32 v236, v154, v162, vcc
	v_cndmask_b32 v237, v155, v163, vcc
	v_add_f32_dpp v234, v244, v234 row_mirror row_mask:0xf bank_mask:0xf bound_ctrl:1
	v_add_f32_dpp v235, v245, v235 row_mirror row_mask:0xf bank_mask:0xf bound_ctrl:1
	v_add_f32_dpp v236, v246, v236 row_mirror row_mask:0xf bank_mask:0xf bound_ctrl:1
	v_add_f32_dpp v237, v247, v237 row_mirror row_mask:0xf bank_mask:0xf bound_ctrl:1
	v_and_b32 v244, 4, v3
	v_cmp_ne_u32 vcc, 0, v244
	v_cndmask_b32 v244, v234, v230, vcc
	v_cndmask_b32 v245, v235, v231, vcc
	v_cndmask_b32 v246, v236, v232, vcc
	v_cndmask_b32 v247, v237, v233, vcc
	v_cndmask_b32 v238, v230, v234, vcc
	v_cndmask_b32 v239, v231, v235, vcc
	v_cndmask_b32 v240, v232, v236, vcc
	v_cndmask_b32 v241, v233, v237, vcc
	v_add_f32_dpp v238, v244, v238 row_half_mirror row_mask:0xf bank_mask:0xf bound_ctrl:1
	v_add_f32_dpp v239, v245, v239 row_half_mirror row_mask:0xf bank_mask:0xf bound_ctrl:1
	v_add_f32_dpp v240, v246, v240 row_half_mirror row_mask:0xf bank_mask:0xf bound_ctrl:1
	v_add_f32_dpp v241, v247, v241 row_half_mirror row_mask:0xf bank_mask:0xf bound_ctrl:1
	v_and_b32 v244, 2, v3
	v_cmp_ne_u32 vcc, 0, v244
	v_cndmask_b32 v244, v240, v238, vcc
	v_cndmask_b32 v245, v241, v239, vcc
	v_cndmask_b32 v242, v238, v240, vcc
	v_cndmask_b32 v243, v239, v241, vcc
	v_add_f32_dpp v242, v244, v242 quad_perm:[2,3,0,1] row_mask:0xf bank_mask:0xf bound_ctrl:1
	v_add_f32_dpp v243, v245, v243 quad_perm:[2,3,0,1] row_mask:0xf bank_mask:0xf bound_ctrl:1
	v_and_b32 v244, 1, v3
	v_cmp_ne_u32 vcc, 0, v244
	v_cndmask_b32 v244, v243, v242, vcc
	v_cndmask_b32 v245, v242, v243, vcc
	s_nop 0
	v_add_f32_dpp v18, v244, v245 quad_perm:[1,0,3,2] row_mask:0xf bank_mask:0xf bound_ctrl:1
	ds_read_b128 v[230:233], v10 offset:29184
	ds_read_b128 v[234:237], v10 offset:29440
	ds_read_b128 v[238:241], v10 offset:29696
	ds_read_b128 v[242:245], v10 offset:29952
	ds_read_b128 v[246:249], v10 offset:30208
	ds_read_b32 v250, v11 offset:29184
	v_add_f32_dpp v146, v146, v146 quad_perm:[1,0,3,2] row_mask:0xf bank_mask:0xf bound_ctrl:1
	v_pk_mul_f32 v[180:181], v[138:139], v[180:181]
	v_pk_fma_f32 v[180:181], v[140:141], v[182:183], v[180:181]
	v_add_f32_dpp v146, v146, v146 quad_perm:[2,3,0,1] row_mask:0xf bank_mask:0xf bound_ctrl:1
	v_add_f32 v148, v180, v181
	v_pk_mul_f32 v[198:199], v[198:199], v[206:207] op_sel_hi:[1,0]
	v_add_f32_dpp v146, v146, v146 row_half_mirror row_mask:0xf bank_mask:0xf bound_ctrl:1
	v_pk_mul_f32 v[200:201], v[200:201], v[206:207] op_sel_hi:[1,0]
	s_waitcnt lgkmcnt(6)
	v_add_f32_dpp v146, v146, v146 row_mirror row_mask:0xf bank_mask:0xf bound_ctrl:1
	v_pk_fma_f32 v[198:199], v[146:147], v[190:191], v[198:199] op_sel_hi:[0,1,1] neg_lo:[1,0,0] neg_hi:[1,0,0]
	v_pk_fma_f32 v[200:201], v[146:147], v[192:193], v[200:201] op_sel_hi:[0,1,1] neg_lo:[1,0,0] neg_hi:[1,0,0]
	v_pk_fma_f32 v[138:139], v[138:139], v[194:195], v[198:199]
	v_pk_fma_f32 v[140:141], v[140:141], v[196:197], v[200:201]
	v_pk_mul_f32 v[144:145], v[138:139], v[208:209]
	v_pk_fma_f32 v[144:145], v[140:141], v[210:211], v[144:145]
	v_add_f32 v146, v144, v145
	ds_read_b128 v[164:167], v10 offset:30720
	ds_read_b128 v[168:171], v10 offset:30976
	ds_read_b128 v[172:175], v10 offset:31232
	ds_read_b128 v[176:179], v10 offset:31488
	ds_read_b128 v[180:183], v10 offset:31744
	ds_read_b32 v184, v11 offset:30720
	v_add_f32_dpp v146, v146, v146 quad_perm:[1,0,3,2] row_mask:0xf bank_mask:0xf bound_ctrl:1
	v_pk_mul_f32 v[202:203], v[138:139], v[202:203]
	v_pk_fma_f32 v[202:203], v[140:141], v[204:205], v[202:203]
	v_add_f32_dpp v146, v146, v146 quad_perm:[2,3,0,1] row_mask:0xf bank_mask:0xf bound_ctrl:1
	v_add_f32 v149, v202, v203
	v_pk_mul_f32 v[220:221], v[220:221], v[228:229] op_sel_hi:[1,0]
	v_add_f32_dpp v146, v146, v146 row_half_mirror row_mask:0xf bank_mask:0xf bound_ctrl:1
	v_pk_mul_f32 v[222:223], v[222:223], v[228:229] op_sel_hi:[1,0]
	s_waitcnt lgkmcnt(6)
	v_add_f32_dpp v146, v146, v146 row_mirror row_mask:0xf bank_mask:0xf bound_ctrl:1
	v_pk_fma_f32 v[220:221], v[146:147], v[212:213], v[220:221] op_sel_hi:[0,1,1] neg_lo:[1,0,0] neg_hi:[1,0,0]
	v_pk_fma_f32 v[222:223], v[146:147], v[214:215], v[222:223] op_sel_hi:[0,1,1] neg_lo:[1,0,0] neg_hi:[1,0,0]
	v_pk_fma_f32 v[138:139], v[138:139], v[216:217], v[220:221]
	v_pk_fma_f32 v[140:141], v[140:141], v[218:219], v[222:223]
	v_pk_mul_f32 v[144:145], v[138:139], v[230:231]
	v_pk_fma_f32 v[144:145], v[140:141], v[232:233], v[144:145]
	v_add_f32 v146, v144, v145
	ds_read_b128 v[186:189], v10 offset:32256
	ds_read_b128 v[190:193], v10 offset:32512
	ds_read_b128 v[194:197], v10 offset:32768
	ds_read_b128 v[198:201], v10 offset:33024
	ds_read_b128 v[202:205], v10 offset:33280
	ds_read_b32 v206, v11 offset:32256
	v_add_f32_dpp v146, v146, v146 quad_perm:[1,0,3,2] row_mask:0xf bank_mask:0xf bound_ctrl:1
	v_pk_mul_f32 v[224:225], v[138:139], v[224:225]
	v_pk_fma_f32 v[224:225], v[140:141], v[226:227], v[224:225]
	v_add_f32_dpp v146, v146, v146 quad_perm:[2,3,0,1] row_mask:0xf bank_mask:0xf bound_ctrl:1
	v_add_f32 v150, v224, v225
	v_pk_mul_f32 v[242:243], v[242:243], v[250:251] op_sel_hi:[1,0]
	v_add_f32_dpp v146, v146, v146 row_half_mirror row_mask:0xf bank_mask:0xf bound_ctrl:1
	v_pk_mul_f32 v[244:245], v[244:245], v[250:251] op_sel_hi:[1,0]
	s_waitcnt lgkmcnt(6)
	v_add_f32_dpp v146, v146, v146 row_mirror row_mask:0xf bank_mask:0xf bound_ctrl:1
	v_pk_fma_f32 v[242:243], v[146:147], v[234:235], v[242:243] op_sel_hi:[0,1,1] neg_lo:[1,0,0] neg_hi:[1,0,0]
	v_pk_fma_f32 v[244:245], v[146:147], v[236:237], v[244:245] op_sel_hi:[0,1,1] neg_lo:[1,0,0] neg_hi:[1,0,0]
	v_pk_fma_f32 v[138:139], v[138:139], v[238:239], v[242:243]
	v_pk_fma_f32 v[140:141], v[140:141], v[240:241], v[244:245]
	v_pk_mul_f32 v[144:145], v[138:139], v[164:165]
	v_pk_fma_f32 v[144:145], v[140:141], v[166:167], v[144:145]
	v_add_f32 v146, v144, v145
	ds_read_b128 v[208:211], v10 offset:33792
	ds_read_b128 v[212:215], v10 offset:34048
	ds_read_b128 v[216:219], v10 offset:34304
	ds_read_b128 v[220:223], v10 offset:34560
	ds_read_b128 v[224:227], v10 offset:34816
	ds_read_b32 v228, v11 offset:33792
	v_add_f32_dpp v146, v146, v146 quad_perm:[1,0,3,2] row_mask:0xf bank_mask:0xf bound_ctrl:1
	v_pk_mul_f32 v[246:247], v[138:139], v[246:247]
	v_pk_fma_f32 v[246:247], v[140:141], v[248:249], v[246:247]
	v_add_f32_dpp v146, v146, v146 quad_perm:[2,3,0,1] row_mask:0xf bank_mask:0xf bound_ctrl:1
	v_add_f32 v151, v246, v247
	v_pk_mul_f32 v[176:177], v[176:177], v[184:185] op_sel_hi:[1,0]
	v_add_f32_dpp v146, v146, v146 row_half_mirror row_mask:0xf bank_mask:0xf bound_ctrl:1
	v_pk_mul_f32 v[178:179], v[178:179], v[184:185] op_sel_hi:[1,0]
	s_waitcnt lgkmcnt(6)
	v_add_f32_dpp v146, v146, v146 row_mirror row_mask:0xf bank_mask:0xf bound_ctrl:1
	v_pk_fma_f32 v[176:177], v[146:147], v[168:169], v[176:177] op_sel_hi:[0,1,1] neg_lo:[1,0,0] neg_hi:[1,0,0]
	v_pk_fma_f32 v[178:179], v[146:147], v[170:171], v[178:179] op_sel_hi:[0,1,1] neg_lo:[1,0,0] neg_hi:[1,0,0]
	v_pk_fma_f32 v[138:139], v[138:139], v[172:173], v[176:177]
	v_pk_fma_f32 v[140:141], v[140:141], v[174:175], v[178:179]
	v_pk_mul_f32 v[144:145], v[138:139], v[186:187]
	v_pk_fma_f32 v[144:145], v[140:141], v[188:189], v[144:145]
	v_add_f32 v146, v144, v145
	ds_read_b128 v[230:233], v10 offset:35328
	ds_read_b128 v[234:237], v10 offset:35584
	ds_read_b128 v[238:241], v10 offset:35840
	ds_read_b128 v[242:245], v10 offset:36096
	ds_read_b128 v[246:249], v10 offset:36352
	ds_read_b32 v250, v11 offset:35328
	v_add_f32_dpp v146, v146, v146 quad_perm:[1,0,3,2] row_mask:0xf bank_mask:0xf bound_ctrl:1
	v_pk_mul_f32 v[180:181], v[138:139], v[180:181]
	v_pk_fma_f32 v[180:181], v[140:141], v[182:183], v[180:181]
	v_add_f32_dpp v146, v146, v146 quad_perm:[2,3,0,1] row_mask:0xf bank_mask:0xf bound_ctrl:1
	v_add_f32 v152, v180, v181
	v_pk_mul_f32 v[198:199], v[198:199], v[206:207] op_sel_hi:[1,0]
	v_add_f32_dpp v146, v146, v146 row_half_mirror row_mask:0xf bank_mask:0xf bound_ctrl:1
	v_pk_mul_f32 v[200:201], v[200:201], v[206:207] op_sel_hi:[1,0]
	s_waitcnt lgkmcnt(6)
	v_add_f32_dpp v146, v146, v146 row_mirror row_mask:0xf bank_mask:0xf bound_ctrl:1
	v_pk_fma_f32 v[198:199], v[146:147], v[190:191], v[198:199] op_sel_hi:[0,1,1] neg_lo:[1,0,0] neg_hi:[1,0,0]
	v_pk_fma_f32 v[200:201], v[146:147], v[192:193], v[200:201] op_sel_hi:[0,1,1] neg_lo:[1,0,0] neg_hi:[1,0,0]
	v_pk_fma_f32 v[138:139], v[138:139], v[194:195], v[198:199]
	v_pk_fma_f32 v[140:141], v[140:141], v[196:197], v[200:201]
	v_pk_mul_f32 v[144:145], v[138:139], v[208:209]
	v_pk_fma_f32 v[144:145], v[140:141], v[210:211], v[144:145]
	v_add_f32 v146, v144, v145
	ds_read_b128 v[164:167], v10 offset:36864
	ds_read_b128 v[168:171], v10 offset:37120
	ds_read_b128 v[172:175], v10 offset:37376
	ds_read_b128 v[176:179], v10 offset:37632
	ds_read_b128 v[180:183], v10 offset:37888
	ds_read_b32 v184, v11 offset:36864
	v_add_f32_dpp v146, v146, v146 quad_perm:[1,0,3,2] row_mask:0xf bank_mask:0xf bound_ctrl:1
	v_pk_mul_f32 v[202:203], v[138:139], v[202:203]
	v_pk_fma_f32 v[202:203], v[140:141], v[204:205], v[202:203]
	v_add_f32_dpp v146, v146, v146 quad_perm:[2,3,0,1] row_mask:0xf bank_mask:0xf bound_ctrl:1
	v_add_f32 v153, v202, v203
	v_pk_mul_f32 v[220:221], v[220:221], v[228:229] op_sel_hi:[1,0]
	v_add_f32_dpp v146, v146, v146 row_half_mirror row_mask:0xf bank_mask:0xf bound_ctrl:1
	v_pk_mul_f32 v[222:223], v[222:223], v[228:229] op_sel_hi:[1,0]
	s_waitcnt lgkmcnt(6)
	v_add_f32_dpp v146, v146, v146 row_mirror row_mask:0xf bank_mask:0xf bound_ctrl:1
	v_pk_fma_f32 v[220:221], v[146:147], v[212:213], v[220:221] op_sel_hi:[0,1,1] neg_lo:[1,0,0] neg_hi:[1,0,0]
	v_pk_fma_f32 v[222:223], v[146:147], v[214:215], v[222:223] op_sel_hi:[0,1,1] neg_lo:[1,0,0] neg_hi:[1,0,0]
	v_pk_fma_f32 v[138:139], v[138:139], v[216:217], v[220:221]
	v_pk_fma_f32 v[140:141], v[140:141], v[218:219], v[222:223]
	v_pk_mul_f32 v[144:145], v[138:139], v[230:231]
	v_pk_fma_f32 v[144:145], v[140:141], v[232:233], v[144:145]
	v_add_f32 v146, v144, v145
	ds_read_b128 v[186:189], v10 offset:38400
	ds_read_b128 v[190:193], v10 offset:38656
	ds_read_b128 v[194:197], v10 offset:38912
	ds_read_b128 v[198:201], v10 offset:39168
	ds_read_b128 v[202:205], v10 offset:39424
	ds_read_b32 v206, v11 offset:38400
	v_add_f32_dpp v146, v146, v146 quad_perm:[1,0,3,2] row_mask:0xf bank_mask:0xf bound_ctrl:1
	v_pk_mul_f32 v[224:225], v[138:139], v[224:225]
	v_pk_fma_f32 v[224:225], v[140:141], v[226:227], v[224:225]
	v_add_f32_dpp v146, v146, v146 quad_perm:[2,3,0,1] row_mask:0xf bank_mask:0xf bound_ctrl:1
	v_add_f32 v154, v224, v225
	v_pk_mul_f32 v[242:243], v[242:243], v[250:251] op_sel_hi:[1,0]
	v_add_f32_dpp v146, v146, v146 row_half_mirror row_mask:0xf bank_mask:0xf bound_ctrl:1
	v_pk_mul_f32 v[244:245], v[244:245], v[250:251] op_sel_hi:[1,0]
	s_waitcnt lgkmcnt(6)
	v_add_f32_dpp v146, v146, v146 row_mirror row_mask:0xf bank_mask:0xf bound_ctrl:1
	v_pk_fma_f32 v[242:243], v[146:147], v[234:235], v[242:243] op_sel_hi:[0,1,1] neg_lo:[1,0,0] neg_hi:[1,0,0]
	v_pk_fma_f32 v[244:245], v[146:147], v[236:237], v[244:245] op_sel_hi:[0,1,1] neg_lo:[1,0,0] neg_hi:[1,0,0]
	v_pk_fma_f32 v[138:139], v[138:139], v[238:239], v[242:243]
	v_pk_fma_f32 v[140:141], v[140:141], v[240:241], v[244:245]
	v_pk_mul_f32 v[144:145], v[138:139], v[164:165]
	v_pk_fma_f32 v[144:145], v[140:141], v[166:167], v[144:145]
	v_add_f32 v146, v144, v145
	ds_read_b128 v[208:211], v10 offset:39936
	ds_read_b128 v[212:215], v10 offset:40192
	ds_read_b128 v[216:219], v10 offset:40448
	ds_read_b128 v[220:223], v10 offset:40704
	ds_read_b128 v[224:227], v10 offset:40960
	ds_read_b32 v228, v11 offset:39936
	v_add_f32_dpp v146, v146, v146 quad_perm:[1,0,3,2] row_mask:0xf bank_mask:0xf bound_ctrl:1
	v_pk_mul_f32 v[246:247], v[138:139], v[246:247]
	v_pk_fma_f32 v[246:247], v[140:141], v[248:249], v[246:247]
	v_add_f32_dpp v146, v146, v146 quad_perm:[2,3,0,1] row_mask:0xf bank_mask:0xf bound_ctrl:1
	v_add_f32 v155, v246, v247
	v_pk_mul_f32 v[176:177], v[176:177], v[184:185] op_sel_hi:[1,0]
	v_add_f32_dpp v146, v146, v146 row_half_mirror row_mask:0xf bank_mask:0xf bound_ctrl:1
	v_pk_mul_f32 v[178:179], v[178:179], v[184:185] op_sel_hi:[1,0]
	s_waitcnt lgkmcnt(6)
	v_add_f32_dpp v146, v146, v146 row_mirror row_mask:0xf bank_mask:0xf bound_ctrl:1
	v_pk_fma_f32 v[176:177], v[146:147], v[168:169], v[176:177] op_sel_hi:[0,1,1] neg_lo:[1,0,0] neg_hi:[1,0,0]
	v_pk_fma_f32 v[178:179], v[146:147], v[170:171], v[178:179] op_sel_hi:[0,1,1] neg_lo:[1,0,0] neg_hi:[1,0,0]
	v_pk_fma_f32 v[138:139], v[138:139], v[172:173], v[176:177]
	v_pk_fma_f32 v[140:141], v[140:141], v[174:175], v[178:179]
	v_pk_mul_f32 v[144:145], v[138:139], v[186:187]
	v_pk_fma_f32 v[144:145], v[140:141], v[188:189], v[144:145]
	v_add_f32 v146, v144, v145
	ds_read_b128 v[230:233], v10 offset:41472
	ds_read_b128 v[234:237], v10 offset:41728
	ds_read_b128 v[238:241], v10 offset:41984
	ds_read_b128 v[242:245], v10 offset:42240
	ds_read_b128 v[246:249], v10 offset:42496
	ds_read_b32 v250, v11 offset:41472
	v_add_f32_dpp v146, v146, v146 quad_perm:[1,0,3,2] row_mask:0xf bank_mask:0xf bound_ctrl:1
	v_pk_mul_f32 v[180:181], v[138:139], v[180:181]
	v_pk_fma_f32 v[180:181], v[140:141], v[182:183], v[180:181]
	v_add_f32_dpp v146, v146, v146 quad_perm:[2,3,0,1] row_mask:0xf bank_mask:0xf bound_ctrl:1
	v_add_f32 v156, v180, v181
	v_pk_mul_f32 v[198:199], v[198:199], v[206:207] op_sel_hi:[1,0]
	v_add_f32_dpp v146, v146, v146 row_half_mirror row_mask:0xf bank_mask:0xf bound_ctrl:1
	v_pk_mul_f32 v[200:201], v[200:201], v[206:207] op_sel_hi:[1,0]
	s_waitcnt lgkmcnt(6)
	v_add_f32_dpp v146, v146, v146 row_mirror row_mask:0xf bank_mask:0xf bound_ctrl:1
	v_pk_fma_f32 v[198:199], v[146:147], v[190:191], v[198:199] op_sel_hi:[0,1,1] neg_lo:[1,0,0] neg_hi:[1,0,0]
	v_pk_fma_f32 v[200:201], v[146:147], v[192:193], v[200:201] op_sel_hi:[0,1,1] neg_lo:[1,0,0] neg_hi:[1,0,0]
	v_pk_fma_f32 v[138:139], v[138:139], v[194:195], v[198:199]
	v_pk_fma_f32 v[140:141], v[140:141], v[196:197], v[200:201]
	v_pk_mul_f32 v[144:145], v[138:139], v[208:209]
	v_pk_fma_f32 v[144:145], v[140:141], v[210:211], v[144:145]
	v_add_f32 v146, v144, v145
	ds_read_b128 v[164:167], v10 offset:43008
	ds_read_b128 v[168:171], v10 offset:43264
	ds_read_b128 v[172:175], v10 offset:43520
	ds_read_b128 v[176:179], v10 offset:43776
	ds_read_b128 v[180:183], v10 offset:44032
	ds_read_b32 v184, v11 offset:43008
	v_add_f32_dpp v146, v146, v146 quad_perm:[1,0,3,2] row_mask:0xf bank_mask:0xf bound_ctrl:1
	v_pk_mul_f32 v[202:203], v[138:139], v[202:203]
	v_pk_fma_f32 v[202:203], v[140:141], v[204:205], v[202:203]
	v_add_f32_dpp v146, v146, v146 quad_perm:[2,3,0,1] row_mask:0xf bank_mask:0xf bound_ctrl:1
	v_add_f32 v157, v202, v203
	v_pk_mul_f32 v[220:221], v[220:221], v[228:229] op_sel_hi:[1,0]
	v_add_f32_dpp v146, v146, v146 row_half_mirror row_mask:0xf bank_mask:0xf bound_ctrl:1
	v_pk_mul_f32 v[222:223], v[222:223], v[228:229] op_sel_hi:[1,0]
	s_waitcnt lgkmcnt(6)
	v_add_f32_dpp v146, v146, v146 row_mirror row_mask:0xf bank_mask:0xf bound_ctrl:1
	v_pk_fma_f32 v[220:221], v[146:147], v[212:213], v[220:221] op_sel_hi:[0,1,1] neg_lo:[1,0,0] neg_hi:[1,0,0]
	v_pk_fma_f32 v[222:223], v[146:147], v[214:215], v[222:223] op_sel_hi:[0,1,1] neg_lo:[1,0,0] neg_hi:[1,0,0]
	v_pk_fma_f32 v[138:139], v[138:139], v[216:217], v[220:221]
	v_pk_fma_f32 v[140:141], v[140:141], v[218:219], v[222:223]
	v_pk_mul_f32 v[144:145], v[138:139], v[230:231]
	v_pk_fma_f32 v[144:145], v[140:141], v[232:233], v[144:145]
	v_add_f32 v146, v144, v145
	ds_read_b128 v[186:189], v10 offset:44544
	ds_read_b128 v[190:193], v10 offset:44800
	ds_read_b128 v[194:197], v10 offset:45056
	ds_read_b128 v[198:201], v10 offset:45312
	ds_read_b128 v[202:205], v10 offset:45568
	ds_read_b32 v206, v11 offset:44544
	v_add_f32_dpp v146, v146, v146 quad_perm:[1,0,3,2] row_mask:0xf bank_mask:0xf bound_ctrl:1
	v_pk_mul_f32 v[224:225], v[138:139], v[224:225]
	v_pk_fma_f32 v[224:225], v[140:141], v[226:227], v[224:225]
	v_add_f32_dpp v146, v146, v146 quad_perm:[2,3,0,1] row_mask:0xf bank_mask:0xf bound_ctrl:1
	v_add_f32 v158, v224, v225
	v_pk_mul_f32 v[242:243], v[242:243], v[250:251] op_sel_hi:[1,0]
	v_add_f32_dpp v146, v146, v146 row_half_mirror row_mask:0xf bank_mask:0xf bound_ctrl:1
	v_pk_mul_f32 v[244:245], v[244:245], v[250:251] op_sel_hi:[1,0]
	s_waitcnt lgkmcnt(6)
	v_add_f32_dpp v146, v146, v146 row_mirror row_mask:0xf bank_mask:0xf bound_ctrl:1
	v_pk_fma_f32 v[242:243], v[146:147], v[234:235], v[242:243] op_sel_hi:[0,1,1] neg_lo:[1,0,0] neg_hi:[1,0,0]
	v_pk_fma_f32 v[244:245], v[146:147], v[236:237], v[244:245] op_sel_hi:[0,1,1] neg_lo:[1,0,0] neg_hi:[1,0,0]
	v_pk_fma_f32 v[138:139], v[138:139], v[238:239], v[242:243]
	v_pk_fma_f32 v[140:141], v[140:141], v[240:241], v[244:245]
	v_pk_mul_f32 v[144:145], v[138:139], v[164:165]
	v_pk_fma_f32 v[144:145], v[140:141], v[166:167], v[144:145]
	v_add_f32 v146, v144, v145
	ds_read_b128 v[208:211], v10 offset:46080
	ds_read_b128 v[212:215], v10 offset:46336
	ds_read_b128 v[216:219], v10 offset:46592
	ds_read_b128 v[220:223], v10 offset:46848
	ds_read_b128 v[224:227], v10 offset:47104
	ds_read_b32 v228, v11 offset:46080
	v_add_f32_dpp v146, v146, v146 quad_perm:[1,0,3,2] row_mask:0xf bank_mask:0xf bound_ctrl:1
	v_pk_mul_f32 v[246:247], v[138:139], v[246:247]
	v_pk_fma_f32 v[246:247], v[140:141], v[248:249], v[246:247]
	v_add_f32_dpp v146, v146, v146 quad_perm:[2,3,0,1] row_mask:0xf bank_mask:0xf bound_ctrl:1
	v_add_f32 v159, v246, v247
	v_pk_mul_f32 v[176:177], v[176:177], v[184:185] op_sel_hi:[1,0]
	v_add_f32_dpp v146, v146, v146 row_half_mirror row_mask:0xf bank_mask:0xf bound_ctrl:1
	v_pk_mul_f32 v[178:179], v[178:179], v[184:185] op_sel_hi:[1,0]
	s_waitcnt lgkmcnt(6)
	v_add_f32_dpp v146, v146, v146 row_mirror row_mask:0xf bank_mask:0xf bound_ctrl:1
	v_pk_fma_f32 v[176:177], v[146:147], v[168:169], v[176:177] op_sel_hi:[0,1,1] neg_lo:[1,0,0] neg_hi:[1,0,0]
	v_pk_fma_f32 v[178:179], v[146:147], v[170:171], v[178:179] op_sel_hi:[0,1,1] neg_lo:[1,0,0] neg_hi:[1,0,0]
	v_pk_fma_f32 v[138:139], v[138:139], v[172:173], v[176:177]
	v_pk_fma_f32 v[140:141], v[140:141], v[174:175], v[178:179]
	v_pk_mul_f32 v[144:145], v[138:139], v[186:187]
	v_pk_fma_f32 v[144:145], v[140:141], v[188:189], v[144:145]
	v_add_f32 v146, v144, v145
	ds_read_b128 v[230:233], v10 offset:47616
	ds_read_b128 v[234:237], v10 offset:47872
	ds_read_b128 v[238:241], v10 offset:48128
	ds_read_b128 v[242:245], v10 offset:48384
	ds_read_b128 v[246:249], v10 offset:48640
	ds_read_b32 v250, v11 offset:47616
	v_add_f32_dpp v146, v146, v146 quad_perm:[1,0,3,2] row_mask:0xf bank_mask:0xf bound_ctrl:1
	v_pk_mul_f32 v[180:181], v[138:139], v[180:181]
	v_pk_fma_f32 v[180:181], v[140:141], v[182:183], v[180:181]
	v_add_f32_dpp v146, v146, v146 quad_perm:[2,3,0,1] row_mask:0xf bank_mask:0xf bound_ctrl:1
	v_add_f32 v160, v180, v181
	v_pk_mul_f32 v[198:199], v[198:199], v[206:207] op_sel_hi:[1,0]
	v_add_f32_dpp v146, v146, v146 row_half_mirror row_mask:0xf bank_mask:0xf bound_ctrl:1
	v_pk_mul_f32 v[200:201], v[200:201], v[206:207] op_sel_hi:[1,0]
	s_waitcnt lgkmcnt(6)
	v_add_f32_dpp v146, v146, v146 row_mirror row_mask:0xf bank_mask:0xf bound_ctrl:1
	v_pk_fma_f32 v[198:199], v[146:147], v[190:191], v[198:199] op_sel_hi:[0,1,1] neg_lo:[1,0,0] neg_hi:[1,0,0]
	v_pk_fma_f32 v[200:201], v[146:147], v[192:193], v[200:201] op_sel_hi:[0,1,1] neg_lo:[1,0,0] neg_hi:[1,0,0]
	v_pk_fma_f32 v[138:139], v[138:139], v[194:195], v[198:199]
	v_pk_fma_f32 v[140:141], v[140:141], v[196:197], v[200:201]
	v_pk_mul_f32 v[144:145], v[138:139], v[208:209]
	v_pk_fma_f32 v[144:145], v[140:141], v[210:211], v[144:145]
	v_add_f32 v146, v144, v145
	s_nop 1
	v_add_f32_dpp v146, v146, v146 quad_perm:[1,0,3,2] row_mask:0xf bank_mask:0xf bound_ctrl:1
	v_pk_mul_f32 v[202:203], v[138:139], v[202:203]
	v_pk_fma_f32 v[202:203], v[140:141], v[204:205], v[202:203]
	v_add_f32_dpp v146, v146, v146 quad_perm:[2,3,0,1] row_mask:0xf bank_mask:0xf bound_ctrl:1
	v_add_f32 v161, v202, v203
	v_pk_mul_f32 v[220:221], v[220:221], v[228:229] op_sel_hi:[1,0]
	v_add_f32_dpp v146, v146, v146 row_half_mirror row_mask:0xf bank_mask:0xf bound_ctrl:1
	v_pk_mul_f32 v[222:223], v[222:223], v[228:229] op_sel_hi:[1,0]
	s_waitcnt lgkmcnt(0)
	v_add_f32_dpp v146, v146, v146 row_mirror row_mask:0xf bank_mask:0xf bound_ctrl:1
	v_pk_fma_f32 v[220:221], v[146:147], v[212:213], v[220:221] op_sel_hi:[0,1,1] neg_lo:[1,0,0] neg_hi:[1,0,0]
	v_pk_fma_f32 v[222:223], v[146:147], v[214:215], v[222:223] op_sel_hi:[0,1,1] neg_lo:[1,0,0] neg_hi:[1,0,0]
	v_pk_fma_f32 v[138:139], v[138:139], v[216:217], v[220:221]
	v_pk_fma_f32 v[140:141], v[140:141], v[218:219], v[222:223]
	v_pk_mul_f32 v[144:145], v[138:139], v[230:231]
	v_pk_fma_f32 v[144:145], v[140:141], v[232:233], v[144:145]
	v_add_f32 v146, v144, v145
	s_nop 1
	v_add_f32_dpp v146, v146, v146 quad_perm:[1,0,3,2] row_mask:0xf bank_mask:0xf bound_ctrl:1
	v_pk_mul_f32 v[224:225], v[138:139], v[224:225]
	v_pk_fma_f32 v[224:225], v[140:141], v[226:227], v[224:225]
	v_add_f32_dpp v146, v146, v146 quad_perm:[2,3,0,1] row_mask:0xf bank_mask:0xf bound_ctrl:1
	v_add_f32 v162, v224, v225
	v_pk_mul_f32 v[242:243], v[242:243], v[250:251] op_sel_hi:[1,0]
	v_add_f32_dpp v146, v146, v146 row_half_mirror row_mask:0xf bank_mask:0xf bound_ctrl:1
	v_pk_mul_f32 v[244:245], v[244:245], v[250:251] op_sel_hi:[1,0]
	s_nop 0
	v_add_f32_dpp v146, v146, v146 row_mirror row_mask:0xf bank_mask:0xf bound_ctrl:1
	v_pk_fma_f32 v[242:243], v[146:147], v[234:235], v[242:243] op_sel_hi:[0,1,1] neg_lo:[1,0,0] neg_hi:[1,0,0]
	v_pk_fma_f32 v[244:245], v[146:147], v[236:237], v[244:245] op_sel_hi:[0,1,1] neg_lo:[1,0,0] neg_hi:[1,0,0]
	v_pk_fma_f32 v[138:139], v[138:139], v[238:239], v[242:243]
	v_pk_fma_f32 v[140:141], v[140:141], v[240:241], v[244:245]
	v_pk_mul_f32 v[246:247], v[138:139], v[246:247]
	v_pk_fma_f32 v[246:247], v[140:141], v[248:249], v[246:247]
	v_add_f32 v163, v246, v247
	s_nop 0
	v_and_b32 v244, 8, v3
	v_cmp_ne_u32 vcc, 0, v244
	v_cndmask_b32 v244, v156, v148, vcc
	v_cndmask_b32 v245, v157, v149, vcc
	v_cndmask_b32 v246, v158, v150, vcc
	v_cndmask_b32 v247, v159, v151, vcc
	v_cndmask_b32 v230, v148, v156, vcc
	v_cndmask_b32 v231, v149, v157, vcc
	v_cndmask_b32 v232, v150, v158, vcc
	v_cndmask_b32 v233, v151, v159, vcc
	v_add_f32_dpp v230, v244, v230 row_mirror row_mask:0xf bank_mask:0xf bound_ctrl:1
	v_add_f32_dpp v231, v245, v231 row_mirror row_mask:0xf bank_mask:0xf bound_ctrl:1
	v_add_f32_dpp v232, v246, v232 row_mirror row_mask:0xf bank_mask:0xf bound_ctrl:1
	v_add_f32_dpp v233, v247, v233 row_mirror row_mask:0xf bank_mask:0xf bound_ctrl:1
	v_cndmask_b32 v244, v160, v152, vcc
	v_cndmask_b32 v245, v161, v153, vcc
	v_cndmask_b32 v246, v162, v154, vcc
	v_cndmask_b32 v247, v163, v155, vcc
	v_cndmask_b32 v234, v152, v160, vcc
	v_cndmask_b32 v235, v153, v161, vcc
	v_cndmask_b32 v236, v154, v162, vcc
	v_cndmask_b32 v237, v155, v163, vcc
	v_add_f32_dpp v234, v244, v234 row_mirror row_mask:0xf bank_mask:0xf bound_ctrl:1
	v_add_f32_dpp v235, v245, v235 row_mirror row_mask:0xf bank_mask:0xf bound_ctrl:1
	v_add_f32_dpp v236, v246, v236 row_mirror row_mask:0xf bank_mask:0xf bound_ctrl:1
	v_add_f32_dpp v237, v247, v237 row_mirror row_mask:0xf bank_mask:0xf bound_ctrl:1
	v_and_b32 v244, 4, v3
	v_cmp_ne_u32 vcc, 0, v244
	v_cndmask_b32 v244, v234, v230, vcc
	v_cndmask_b32 v245, v235, v231, vcc
	v_cndmask_b32 v246, v236, v232, vcc
	v_cndmask_b32 v247, v237, v233, vcc
	v_cndmask_b32 v238, v230, v234, vcc
	v_cndmask_b32 v239, v231, v235, vcc
	v_cndmask_b32 v240, v232, v236, vcc
	v_cndmask_b32 v241, v233, v237, vcc
	v_add_f32_dpp v238, v244, v238 row_half_mirror row_mask:0xf bank_mask:0xf bound_ctrl:1
	v_add_f32_dpp v239, v245, v239 row_half_mirror row_mask:0xf bank_mask:0xf bound_ctrl:1
	v_add_f32_dpp v240, v246, v240 row_half_mirror row_mask:0xf bank_mask:0xf bound_ctrl:1
	v_add_f32_dpp v241, v247, v241 row_half_mirror row_mask:0xf bank_mask:0xf bound_ctrl:1
	v_and_b32 v244, 2, v3
	v_cmp_ne_u32 vcc, 0, v244
	v_cndmask_b32 v244, v240, v238, vcc
	v_cndmask_b32 v245, v241, v239, vcc
	v_cndmask_b32 v242, v238, v240, vcc
	v_cndmask_b32 v243, v239, v241, vcc
	v_add_f32_dpp v242, v244, v242 quad_perm:[2,3,0,1] row_mask:0xf bank_mask:0xf bound_ctrl:1
	v_add_f32_dpp v243, v245, v243 quad_perm:[2,3,0,1] row_mask:0xf bank_mask:0xf bound_ctrl:1
	v_and_b32 v244, 1, v3
	v_cmp_ne_u32 vcc, 0, v244
	v_cndmask_b32 v244, v243, v242, vcc
	v_cndmask_b32 v245, v242, v243, vcc
	s_nop 0
	v_add_f32_dpp v19, v244, v245 quad_perm:[1,0,3,2] row_mask:0xf bank_mask:0xf bound_ctrl:1
	v_mov_b32 v2, v138
	v_mov_b32 v13, v139
	v_mov_b32 v12, v140
	v_mov_b32 v8, v141

; #define SCAN_BAR() asm volatile("s_barrier" ::: "memory")
; __device__ __forceinline__ void scan_unit(const Ctx& C0, const float* scn, int T, int quarter, const float* S0, float* Sout, unsigned char* obase, int mode) {
;     ...
;         for (int k = 0; k < nch; ++k) {
;             const unsigned aq = (unsigned)(size_t)(C.lds + (k & 1) * SLOT_B) + 16u * (unsigned)q, av = (unsigned)(size_t)(C.lds + (k & 1) * SLOT_B) + (320u + (unsigned)irow) * 4u;
;             float osel0, osel1;
;             asm volatile(SCAN_CHUNK_ASM : "+v"(S0x), "+v"(S1x), "+v"(S2x), "+v"(S3x), "=&v"(osel0), "=&v"(osel1) : "v"(aq), "v"(av), "v"(q) : SCAN_CHUNK_CLOBBERS, "memory");
;             if (mode == 0) { *(float*)(obase + (size_t)(k * 32 + q) * UPITCH_B + rl * 4) = osel0; *(float*)(obase + (size_t)(k * 32 + 16 + q) * UPITCH_B + rl * 4) = osel1; }
;             SCAN_BAR();
;         }
;         if (mode == 0) *(f32x4*)(Sout + irow * 64 + 4 * q) = (f32x4){S0x, S1x, S2x, S3x};
	s_addc_u32 s1, s1, 0
	v_add_co_u32_e32 v16, vcc, s8, v14
	s_cmp_lg_u32 s0, 0x5600000
	s_nop 0
	v_addc_co_u32_e32 v17, vcc, 0, v15, vcc
	v_add_co_u32_e32 v14, vcc, 0xfcaa000, v14
	global_store_dword v[16:17], v18, off offset:768
	s_nop 0
	v_addc_co_u32_e32 v15, vcc, 0, v15, vcc
	global_store_dword v[14:15], v19, off offset:768
	s_barrier
	s_cbranch_scc1 .LBB0_685
	v_readlane_b32 s0, v255, 46
	s_add_i32 s0, s3, s0
	s_ashr_i32 s1, s0, 31
	s_lshl_b64 s[0:1], s[0:1], 17
	v_readlane_b32 s3, v253, 26
	s_add_u32 s0, s3, s0
	v_readlane_b32 s3, v253, 27
	s_addc_u32 s1, s3, s1
	s_lshl_b32 s2, s2, 14
	s_add_u32 s0, s0, s2
	s_addc_u32 s1, s1, 0
	v_lshlrev_b32_e32 v0, 8, v0
	v_lshl_add_u64 v[6:7], s[0:1], 0, v[0:1]
	v_mov_b32_e32 v5, v1
	v_lshl_add_u64 v[6:7], v[6:7], 0, v[4:5]
	v_mov_b32_e32 v3, v13
	v_mov_b32_e32 v4, v12
	v_mov_b32_e32 v5, v8
	global_store_dwordx4 v[6:7], v[2:5], off

; __global__ void __launch_bounds__(NWAVES * 64, 2) hybrid_fwd(Args A) {
;     ...
;                 const bool split = C.G >= 192; bool go = (s == 4); int k0 = split ? KSPLIT : 0, kl = D - k0, gg = C.G, cc = C.bid, mrows = M; size_t roff = 0;
;                 if (s == 2) { go = phase_mixers(A, C, l, rep ? DUP_UN : 7); k0 = 0; kl = KSPLIT; gg = C.G - 128; cc = C.bid - 128; mrows = MP; }
;                 if (s == 3) { phase_post(A, C, l, split ? 8 : 0); go = split && C.bid < 8 && !rep; k0 = 0; kl = KSPLIT; gg = 8; cc = C.bid; mrows = MS; roff = (size_t)MP * D; }
;                 if (go) { pg8::Gemm g{WS_PTR(const bf16, WS_XN) + roff + k0, WS_PTR(const bf16, WS_WOUTT) + (size_t)l * D * D + k0, mrows, D, kl, D}; pg8::StaticOrder S; S.init(mrows, D, gg, cc);
.LBB0_1181:
.LBB0_1182:
	s_mov_b32 s8, 0
	s_movk_i32 s3, 0x380
	s_movk_i32 s11, 0x80
	v_readlane_b32 s30, v253, 35
	v_readlane_b32 s17, v253, 34

; __global__ void __launch_bounds__(NWAVES * 64, 2) hybrid_fwd(Args A) {
;     ...
;                 if (s == 3) { phase_post(A, C, l, split ? 8 : 0); go = split && C.bid < 8 && !rep; k0 = 0; kl = KSPLIT; gg = 8; cc = C.bid; mrows = MS; roff = (size_t)MP * D; }
;                 if (go) { pg8::Gemm g{WS_PTR(const bf16, WS_XN) + roff + k0, WS_PTR(const bf16, WS_WOUTT) + (size_t)l * D * D + k0, mrows, D, kl, D}; pg8::StaticOrder S; S.init(mrows, D, gg, cc);
.LBB0_1188:
	v_readlane_b32 s52, v253, 36
	s_mov_b32 s8, 0
	s_movk_i32 s3, 0x380
	s_mov_b32 s17, 8
	s_mov_b32 s11, 1
	s_mov_b64 s[40:41], 0x4000000
	v_readlane_b32 s30, v253, 0
	v_readlane_b32 s53, v253, 37
